# dn_chunk: final u/w stores transposed through LDS into 16-byte stores
# baseline (speedup 1.0000x reference)
.LBB0_229:
	s_or_b64 exec, exec, s[2:3]
	v_mul_lo_u32 v160, v118, s72
	s_barrier
	ds_write_b128 v160, v[242:245] offset:32768
	ds_write_b128 v160, v[242:245] offset:32784
	ds_write_b128 v160, v[242:245] offset:32800
	ds_write_b128 v160, v[242:245] offset:32816
	ds_write_b128 v160, v[242:245] offset:32832
	ds_write_b128 v160, v[242:245] offset:32848
	ds_write_b128 v160, v[242:245] offset:32864
	ds_write_b128 v160, v[242:245] offset:32880
	ds_read_b128 v[0:3], v117 offset:256
	ds_read_b128 v[78:81], v117 offset:512
	ds_write_b128 v160, v[242:245] offset:32896
	v_lshlrev_b32_e32 v91, 8, v35
	ds_read_b128 v[82:85], v117 offset:768
	ds_read_b128 v[182:185], v117 offset:1024
	ds_read_b128 v[70:73], v117 offset:1280
	ds_read_b128 v[86:89], v117 offset:1296
	ds_read_b128 v[50:53], v117 offset:1536
	ds_read_b128 v[42:45], v117 offset:1552
	ds_read_b128 v[38:41], v117 offset:1792
	ds_read_b128 v[34:37], v117 offset:1808
	v_mov_b32_e32 v4, v145
	v_mov_b32_e32 v5, v159
	s_waitcnt lgkmcnt(10)
	v_mul_f32_e32 v6, v159, v1
	v_pk_fma_f32 v[0:1], v[4:5], v[0:1], v[6:7] op_sel_hi:[1,1,0]
	s_waitcnt lgkmcnt(4)
	v_mov_b32_e32 v212, v87
	v_pk_fma_f32 v[0:1], v[154:155], v[2:3], v[0:1]
	v_mul_f32_e32 v2, v155, v3
	v_pk_add_f32 v[206:207], v[2:3], v[0:1] op_sel_hi:[0,1]
	v_mov_b32_e32 v213, v70
	v_mov_b32_e32 v87, v71
	s_waitcnt lgkmcnt(3)
	v_mov_b32_e32 v164, v52
	s_waitcnt lgkmcnt(2)
	v_mov_b32_e32 v165, v44
	v_mov_b32_e32 v44, v53
	v_mov_b32_e32 v170, v51
	v_mov_b32_e32 v171, v42
	v_mov_b32_e32 v51, v43
	s_waitcnt lgkmcnt(1)
	v_mov_b32_e32 v168, v39
	s_waitcnt lgkmcnt(0)
	v_mov_b32_e32 v169, v34
	v_mov_b32_e32 v39, v35
	v_mov_b32_e32 v172, v40
	v_mov_b32_e32 v173, v36
	v_mov_b32_e32 v36, v41
	ds_read_b128 v[56:59], v117 offset:2048
	ds_read_b128 v[52:55], v117 offset:2064
	ds_read_b128 v[186:189], v117 offset:2304
	ds_read_b128 v[178:181], v117 offset:2320
	ds_read_b128 v[32:35], v117 offset:2336
	ds_read_b128 v[190:193], v117 offset:2560
	ds_read_b128 v[194:197], v117 offset:2576
	ds_read_b128 v[28:31], v117 offset:2592
	ds_read_b128 v[198:201], v117 offset:2816
	ds_read_b128 v[20:23], v117 offset:2832
	ds_read_b128 v[24:27], v117 offset:2848
	ds_read_b128 v[202:205], v117 offset:3072
	ds_read_b128 v[246:249], v117 offset:3088
	ds_read_b128 v[16:19], v117 offset:3104
	ds_read_b128 v[64:67], v117 offset:3328
	ds_read_b128 v[60:63], v117 offset:3344
	ds_read_b128 v[12:15], v117 offset:3360
	ds_read_b128 v[8:11], v117 offset:3376
	ds_read_b128 v[46:49], v117 offset:3840
	ds_read_b128 v[40:43], v117 offset:3856
	ds_read_b128 v[74:77], v117 offset:3584
	ds_read_b128 v[68:71], v117 offset:3600
	ds_read_b128 v[4:7], v117 offset:3616
	ds_read_b128 v[0:3], v117 offset:3632
	v_mov_b32_e32 v214, v88
	v_mov_b32_e32 v215, v72
	v_mov_b32_e32 v72, v89
	s_waitcnt lgkmcnt(5)
	v_mov_b32_e32 v88, v47
	s_waitcnt lgkmcnt(4)
	v_mov_b32_e32 v89, v40
	v_mov_b32_e32 v47, v41
	v_pk_add_f32 v[40:41], v[158:159], v[206:207] op_sel:[1,0] op_sel_hi:[0,1] neg_lo:[0,1] neg_hi:[0,1]
	v_mov_b32_e32 v162, v48
	v_mov_b32_e32 v163, v42
	v_mov_b32_e32 v42, v49
	v_pk_mov_b32 v[48:49], v[144:145], v[40:41] op_sel:[1,0]
	v_mul_f32_e32 v206, v79, v40
	v_pk_fma_f32 v[78:79], v[78:79], v[48:49], v[206:207] op_sel_hi:[1,1,0]
	v_mov_b32_e32 v218, v20
	v_pk_fma_f32 v[78:79], v[154:155], v[80:81], v[78:79]
	v_mul_f32_e32 v80, v155, v81
	v_pk_add_f32 v[78:79], v[80:81], v[78:79] op_sel_hi:[0,1]
	v_mul_f32_e32 v80, v83, v40
	v_pk_fma_f32 v[80:81], v[82:83], v[48:49], v[80:81] op_sel_hi:[1,1,0]
	v_mul_f32_e32 v82, v183, v40
	v_pk_fma_f32 v[182:183], v[182:183], v[48:49], v[82:83] op_sel_hi:[1,1,0]
	v_mul_f32_e32 v82, v40, v187
	v_pk_fma_f32 v[186:187], v[48:49], v[186:187], v[82:83] op_sel_hi:[1,1,0]
	v_mul_f32_e32 v82, v40, v191
	v_pk_fma_f32 v[190:191], v[48:49], v[190:191], v[82:83] op_sel_hi:[1,1,0]
	v_mul_f32_e32 v82, v40, v199
	v_pk_fma_f32 v[198:199], v[48:49], v[198:199], v[82:83] op_sel_hi:[1,1,0]
	v_mul_f32_e32 v82, v40, v203
	v_pk_fma_f32 v[202:203], v[48:49], v[202:203], v[82:83] op_sel_hi:[1,1,0]
	v_pk_add_f32 v[48:49], v[154:155], v[78:79] neg_lo:[0,1] neg_hi:[0,1]
	v_mov_b32_e32 v219, v24
	v_mov_b32_e32 v49, v155
	v_pk_fma_f32 v[78:79], v[48:49], v[84:85], v[80:81]
	v_mul_f32_e32 v80, v155, v85
	v_pk_add_f32 v[206:207], v[80:81], v[78:79] op_sel_hi:[0,1]
	v_pk_add_f32 v[154:155], v[154:155], v[206:207] op_sel:[1,0] op_sel_hi:[0,1] neg_lo:[0,1] neg_hi:[0,1]
	v_mov_b32_e32 v49, v154
	v_pk_fma_f32 v[182:183], v[184:185], v[48:49], v[182:183]
	v_mul_f32_e32 v184, v185, v154
	v_mov_b32_e32 v24, v21
	v_pk_add_f32 v[20:21], v[182:183], v[184:185] op_sel_hi:[1,0]
	v_mov_b32_e32 v175, v28
	v_pk_add_f32 v[20:21], v[158:159], v[20:21] neg_lo:[0,1] neg_hi:[0,1]
	v_mov_b32_e32 v28, v195
	v_mov_b32_e32 v21, v40
	v_mov_b32_e32 v195, v33
	v_mov_b32_e32 v217, v32
	v_pk_mul_f32 v[32:33], v[86:87], v[20:21]
	v_mov_b32_e32 v158, v58
	v_mov_b32_e32 v159, v54
	v_mov_b32_e32 v54, v59
	v_pk_fma_f32 v[32:33], v[144:145], v[212:213], v[32:33]
	v_mov_b32_e32 v58, v156
	v_mov_b32_e32 v59, v48
	v_pk_fma_f32 v[32:33], v[214:215], v[58:59], v[32:33]
	v_pk_mov_b32 v[58:59], v[156:157], v[154:155] op_sel:[1,0]
	s_waitcnt lgkmcnt(3)
	v_mov_b32_e32 v182, v76
	v_pk_fma_f32 v[32:33], v[72:73], v[58:59], v[32:33]
	v_mov_b32_e32 v41, v20
	v_pk_add_f32 v[58:59], v[144:145], v[32:33] op_sel:[0,1] op_sel_hi:[1,0] neg_lo:[0,1] neg_hi:[0,1]
	v_pk_fma_f32 v[72:73], v[48:49], v[188:189], v[186:187]
	v_pk_add_f32 v[58:59], v[58:59], v[32:33] neg_lo:[0,1] neg_hi:[0,1]
	v_mul_f32_e32 v76, v154, v189
	v_pk_mov_b32 v[32:33], v[144:145], v[58:59] op_sel:[1,0]
	v_mov_b32_e32 v86, v75
	v_pk_mul_f32 v[50:51], v[32:33], v[50:51]
	s_waitcnt lgkmcnt(2)
	v_mov_b32_e32 v87, v68
	v_mov_b32_e32 v75, v69
	v_mov_b32_e32 v68, v48
	v_mov_b32_e32 v69, v156
	v_pk_add_f32 v[72:73], v[72:73], v[76:77] op_sel_hi:[1,0]
	v_pk_fma_f32 v[50:51], v[40:41], v[170:171], v[50:51]
	v_mov_b32_e32 v183, v70
	v_mov_b32_e32 v70, v77
	v_mov_b32_e32 v155, v157
	v_pk_add_f32 v[76:77], v[150:151], v[72:73] op_sel:[1,0] op_sel_hi:[0,1] neg_lo:[0,1] neg_hi:[0,1]
	v_pk_fma_f32 v[72:73], v[48:49], v[192:193], v[190:191]
	v_mul_f32_e32 v184, v154, v193
	v_pk_fma_f32 v[50:51], v[164:165], v[68:69], v[50:51]
	v_pk_add_f32 v[72:73], v[184:185], v[72:73] op_sel_hi:[0,1]
	v_pk_fma_f32 v[44:45], v[44:45], v[154:155], v[50:51]
	v_pk_add_f32 v[184:185], v[152:153], v[72:73] neg_lo:[0,1] neg_hi:[0,1]
	v_pk_fma_f32 v[72:73], v[48:49], v[200:201], v[198:199]
	v_mul_f32_e32 v186, v154, v201
	v_pk_add_f32 v[50:51], v[156:157], v[44:45] neg_lo:[0,1] neg_hi:[0,1]
	v_pk_add_f32 v[72:73], v[186:187], v[72:73] op_sel_hi:[0,1]
	v_pk_add_f32 v[68:69], v[50:51], v[44:45] op_sel:[0,1] op_sel_hi:[1,0] neg_lo:[0,1] neg_hi:[0,1]
	v_pk_mul_f32 v[38:39], v[32:33], v[38:39]
	v_pk_add_f32 v[186:187], v[152:153], v[72:73] op_sel:[1,0] op_sel_hi:[0,1] neg_lo:[0,1] neg_hi:[0,1]
	v_pk_fma_f32 v[72:73], v[48:49], v[204:205], v[202:203]
	v_pk_fma_f32 v[38:39], v[40:41], v[168:169], v[38:39]
	v_mov_b32_e32 v49, v68
	v_pk_fma_f32 v[38:39], v[172:173], v[48:49], v[38:39]
	v_mov_b32_e32 v206, v23
	v_mov_b32_e32 v207, v27
	v_mov_b32_e32 v23, v26
	v_mov_b32_e32 v26, v57
	v_mov_b32_e32 v27, v52
	v_mov_b32_e32 v52, v145
	v_mul_f32_e32 v188, v154, v205
	v_pk_fma_f32 v[36:37], v[36:37], v[154:155], v[38:39]
	v_mov_b32_e32 v57, v58
	v_pk_add_f32 v[72:73], v[188:189], v[72:73] op_sel_hi:[0,1]
	v_pk_add_f32 v[38:39], v[156:157], v[36:37] op_sel:[1,0] op_sel_hi:[0,1] neg_lo:[0,1] neg_hi:[0,1]
	v_pk_mul_f32 v[52:53], v[52:53], v[56:57]
	v_pk_add_f32 v[188:189], v[148:149], v[72:73] neg_lo:[0,1] neg_hi:[0,1]
	v_pk_add_f32 v[72:73], v[38:39], v[36:37] op_sel:[0,1] op_sel_hi:[1,0] neg_lo:[0,1] neg_hi:[0,1]
	v_pk_fma_f32 v[26:27], v[40:41], v[26:27], v[52:53]
	v_mov_b32_e32 v155, v72
	v_pk_fma_f32 v[26:27], v[158:159], v[48:49], v[26:27]
	v_mov_b32_e32 v36, v65
	v_pk_fma_f32 v[26:27], v[54:55], v[154:155], v[26:27]
	v_mov_b32_e32 v37, v60
	v_pk_add_f32 v[52:53], v[150:151], v[26:27] neg_lo:[0,1] neg_hi:[0,1]
	v_mov_b32_e32 v65, v61
	v_pk_add_f32 v[60:61], v[52:53], v[26:27] op_sel:[0,1] op_sel_hi:[1,0] neg_lo:[0,1] neg_hi:[0,1]
	v_mov_b32_e32 v216, v179
	v_mov_b32_e32 v59, v60
	v_mov_b32_e32 v174, v194
	v_mov_b32_e32 v194, v178
	v_mov_b32_e32 v21, v151
	v_pk_mul_f32 v[26:27], v[216:217], v[58:59]
	v_mov_b32_e32 v166, v196
	v_mov_b32_e32 v167, v30
	v_mov_b32_e32 v30, v197
	v_mov_b32_e32 v196, v180
	v_mov_b32_e32 v197, v34
	v_mov_b32_e32 v69, v152
	v_pk_fma_f32 v[26:27], v[194:195], v[20:21], v[26:27]
	v_mov_b32_e32 v34, v181
	v_pk_mul_f32 v[44:45], v[32:33], v[74:75]
	v_mov_b32_e32 v73, v153
	v_pk_fma_f32 v[26:27], v[196:197], v[68:69], v[26:27]
	v_pk_fma_f32 v[44:45], v[40:41], v[86:87], v[44:45]
	v_pk_fma_f32 v[26:27], v[34:35], v[72:73], v[26:27]
	v_pk_fma_f32 v[44:45], v[48:49], v[182:183], v[44:45]
	v_pk_add_f32 v[34:35], v[76:77], v[26:27] neg_lo:[0,1] neg_hi:[0,1]
	v_pk_fma_f32 v[44:45], v[154:155], v[70:71], v[44:45]
	v_pk_add_f32 v[70:71], v[34:35], v[26:27] op_sel:[0,1] op_sel_hi:[1,0] neg_lo:[0,1] neg_hi:[0,1]
	v_mov_b32_e32 v21, v60
	v_mov_b32_e32 v59, v70
	v_pk_mul_f32 v[26:27], v[28:29], v[58:59]
	v_pk_mul_f32 v[24:25], v[24:25], v[58:59]
	v_pk_fma_f32 v[26:27], v[174:175], v[20:21], v[26:27]
	v_pk_fma_f32 v[24:25], v[20:21], v[218:219], v[24:25]
	v_pk_fma_f32 v[26:27], v[166:167], v[68:69], v[26:27]
	v_mov_b32_e32 v179, v16
	v_pk_fma_f32 v[26:27], v[30:31], v[72:73], v[26:27]
	v_mov_b32_e32 v16, v247
	v_pk_add_f32 v[28:29], v[184:185], v[26:27] neg_lo:[0,1] neg_hi:[0,1]
	v_mov_b32_e32 v178, v246
	v_pk_add_f32 v[76:77], v[28:29], v[26:27] op_sel:[0,1] op_sel_hi:[1,0] neg_lo:[0,1] neg_hi:[0,1]
	v_pk_mul_f32 v[16:17], v[16:17], v[58:59]
	v_mov_b32_e32 v69, v76
	v_pk_fma_f32 v[22:23], v[22:23], v[68:69], v[24:25]
	v_mov_b32_e32 v180, v248
	v_pk_fma_f32 v[22:23], v[206:207], v[72:73], v[22:23]
	v_mov_b32_e32 v181, v18
	v_pk_add_f32 v[24:25], v[186:187], v[22:23] neg_lo:[0,1] neg_hi:[0,1]
	v_pk_fma_f32 v[16:17], v[20:21], v[178:179], v[16:17]
	v_pk_add_f32 v[86:87], v[24:25], v[22:23] op_sel:[0,1] op_sel_hi:[1,0] neg_lo:[0,1] neg_hi:[0,1]
	v_mov_b32_e32 v18, v249
	v_pk_fma_f32 v[16:17], v[180:181], v[68:69], v[16:17]
	v_mov_b32_e32 v73, v86
	v_pk_fma_f32 v[16:17], v[18:19], v[72:73], v[16:17]
	v_pk_mul_f32 v[38:39], v[32:33], v[64:65]
	v_pk_mul_f32 v[32:33], v[32:33], v[46:47]
	v_pk_add_f32 v[18:19], v[188:189], v[16:17] neg_lo:[0,1] neg_hi:[0,1]
	v_pk_fma_f32 v[32:33], v[40:41], v[88:89], v[32:33]
	v_pk_add_f32 v[88:89], v[18:19], v[16:17] op_sel:[0,1] op_sel_hi:[1,0] neg_lo:[0,1] neg_hi:[0,1]
	v_pk_fma_f32 v[36:37], v[40:41], v[36:37], v[38:39]
	v_mov_b32_e32 v38, v66
	v_mov_b32_e32 v39, v62
	v_mov_b32_e32 v16, v12
	v_mov_b32_e32 v12, v13
	v_mov_b32_e32 v13, v8
	v_mov_b32_e32 v71, v88
	v_pk_fma_f32 v[36:37], v[48:49], v[38:39], v[36:37]
	v_mov_b32_e32 v62, v67
	v_mov_b32_e32 v17, v9
	v_mov_b32_e32 v61, v149
	v_pk_mul_f32 v[8:9], v[12:13], v[70:71]
	v_pk_fma_f32 v[36:37], v[154:155], v[62:63], v[36:37]
	v_mov_b32_e32 v18, v14
	v_mov_b32_e32 v19, v10
	v_mov_b32_e32 v77, v146
	v_pk_fma_f32 v[8:9], v[16:17], v[60:61], v[8:9]
	v_pk_add_f32 v[38:39], v[148:149], v[36:37] op_sel:[1,0] op_sel_hi:[0,1] neg_lo:[0,1] neg_hi:[0,1]
	v_mov_b32_e32 v10, v15
	v_mov_b32_e32 v87, v147
	v_pk_fma_f32 v[8:9], v[18:19], v[76:77], v[8:9]
	v_pk_add_f32 v[36:37], v[38:39], v[36:37] op_sel:[0,1] op_sel_hi:[1,0] neg_lo:[0,1] neg_hi:[0,1]
	v_pk_fma_f32 v[8:9], v[10:11], v[86:87], v[8:9]
	ds_read_b128 v[82:85], v117 offset:3872
	ds_read_b128 v[78:81], v117 offset:3888
	v_pk_add_f32 v[10:11], v[36:37], v[8:9] neg_lo:[0,1] neg_hi:[0,1]
	v_mov_b32_e32 v61, v88
	v_pk_add_f32 v[148:149], v[10:11], v[8:9] op_sel:[0,1] op_sel_hi:[1,0] neg_lo:[0,1] neg_hi:[0,1]
	s_waitcnt lgkmcnt(2)
	v_mov_b32_e32 v9, v2
	v_mov_b32_e32 v2, v7
	v_mov_b32_e32 v7, v0
	v_mov_b32_e32 v0, v5
	v_mov_b32_e32 v71, v148
	v_mov_b32_e32 v8, v6
	v_mov_b32_e32 v6, v4
	v_pk_mul_f32 v[0:1], v[0:1], v[70:71]
	v_pk_add_f32 v[50:51], v[146:147], v[44:45] neg_lo:[0,1] neg_hi:[0,1]
	v_pk_fma_f32 v[0:1], v[6:7], v[60:61], v[0:1]
	v_pk_add_f32 v[38:39], v[50:51], v[44:45] op_sel:[0,1] op_sel_hi:[1,0] neg_lo:[0,1] neg_hi:[0,1]
	v_pk_fma_f32 v[0:1], v[8:9], v[76:77], v[0:1]
	v_pk_fma_f32 v[32:33], v[48:49], v[162:163], v[32:33]
	v_pk_fma_f32 v[0:1], v[2:3], v[86:87], v[0:1]
	v_pk_fma_f32 v[32:33], v[154:155], v[42:43], v[32:33]
	v_pk_add_f32 v[2:3], v[38:39], v[0:1] neg_lo:[0,1] neg_hi:[0,1]
	v_lshl_or_b32 v157, v116, 2, v91
	v_pk_add_f32 v[150:151], v[2:3], v[0:1] op_sel:[0,1] op_sel_hi:[1,0] neg_lo:[0,1] neg_hi:[0,1]
	s_waitcnt lgkmcnt(0)
	v_mov_b32_e32 v1, v78
	v_mov_b32_e32 v78, v83
	v_mov_b32_e32 v0, v82
	v_pk_mul_f32 v[2:3], v[78:79], v[70:71]
	v_mov_b32_e32 v77, v150
	v_pk_fma_f32 v[0:1], v[0:1], v[60:61], v[2:3]
	v_mov_b32_e32 v2, v84
	v_mov_b32_e32 v3, v80
	v_pk_fma_f32 v[0:1], v[2:3], v[76:77], v[0:1]
	v_mov_b32_e32 v80, v85
	v_sub_f32_e32 v2, v147, v32
	v_pk_fma_f32 v[0:1], v[80:81], v[86:87], v[0:1]
	v_sub_f32_e32 v2, v2, v33
	v_sub_f32_e32 v0, v2, v0
	v_sub_f32_e32 v59, v0, v1
	v_cvt_pk_bf16_f32 v0, v145, v40
	v_cvt_pk_bf16_f32 v1, v48, v154
	v_cvt_pk_bf16_f32 v2, v20, v58
	v_cvt_pk_bf16_f32 v3, v68, v72
	ds_write_b128 v160, v[0:3] offset:32768
	v_cvt_pk_bf16_f32 v0, v60, v70
	v_cvt_pk_bf16_f32 v1, v76, v86
	v_cvt_pk_bf16_f32 v2, v88, v148
	v_cvt_pk_bf16_f32 v3, v150, v59
	ds_write_b128 v160, v[0:3] offset:32784
	s_waitcnt lgkmcnt(0)
	ds_read_b128 v[0:3], v157 offset:4096
	ds_read_b128 v[4:7], v157 offset:4112
	v_and_b32_e32 v8, 0xffffffcf, v118
	v_cmp_gt_u32_e64 s[4:5], 32, v239
	v_mad_u64_u32 v[64:65], s[2:3], v8, s72, v[176:177]
	s_waitcnt lgkmcnt(1)
	v_cndmask_b32_e64 v3, 0, v3, s[4:5]
	v_cndmask_b32_e64 v2, 0, v2, s[4:5]
	v_cndmask_b32_e64 v1, 0, v1, s[4:5]
	v_cndmask_b32_e64 v0, 0, v0, s[4:5]
	s_waitcnt lgkmcnt(0)
	v_cndmask_b32_e64 v7, 0, v7, s[4:5]
	v_cndmask_b32_e64 v6, 0, v6, s[4:5]
	v_cndmask_b32_e64 v5, 0, v5, s[4:5]
	v_cndmask_b32_e64 v4, 0, v4, s[4:5]
	v_cvt_pk_bf16_f32 v0, v0, v1
	v_cvt_pk_bf16_f32 v1, v2, v3
	v_cvt_pk_bf16_f32 v2, v4, v5
	v_cvt_pk_bf16_f32 v3, v6, v7
	ds_read_b128 v[4:7], v64 offset:32768
	v_lshl_or_b32 v151, v8, 6, v176
	s_waitcnt lgkmcnt(0)
	v_mfma_f32_16x16x32_bf16 v[4:7], v[0:3], v[4:7], 0
	v_or_b32_e32 v8, 48, v118
	v_mad_u64_u32 v[66:67], s[2:3], v8, s72, v[176:177]
	s_nop 5
	ds_write_b128 v151, v[4:7] offset:16384
	ds_read_b128 v[4:7], v64 offset:35072
	s_waitcnt lgkmcnt(0)
	v_mfma_f32_16x16x32_bf16 v[4:7], v[0:3], v[4:7], 0
	v_lshl_or_b32 v156, v8, 6, v176
	v_mad_u64_u32 v[62:63], s[2:3], v118, s73, v[160:161]
	s_nop 5
	ds_write_b128 v151, v[4:7] offset:17408
	ds_read_b128 v[4:7], v64 offset:37376
	s_waitcnt lgkmcnt(0)
	v_mfma_f32_16x16x32_bf16 v[4:7], v[0:3], v[4:7], 0
	v_cvt_pk_bf16_f32 v63, v145, s0
	v_cvt_pk_bf16_f32 v67, v48, s0
	v_cvt_pk_bf16_f32 v149, v20, s0
	s_nop 4
	ds_write_b128 v151, v[4:7] offset:18432
	ds_read_b128 v[4:7], v66 offset:32768
	s_waitcnt lgkmcnt(0)
	v_mfma_f32_16x16x32_bf16 v[0:3], v[0:3], v[4:7], 0
	v_cvt_pk_bf16_f32 v91, v154, s0
	v_cvt_pk_bf16_f32 v65, v40, s0
	s_add_i32 s46, s46, s95
	s_nop 4
	ds_write_b128 v156, v[0:3] offset:16384
	s_waitcnt lgkmcnt(0)
	ds_read_b128 v[54:57], v62 offset:16384
	ds_read_b128 v[0:3], v62 offset:16400
	ds_read_b128 v[162:165], v117 offset:4416
	ds_read_b128 v[4:7], v62 offset:16416
	ds_read_b128 v[144:147], v62 offset:16432
	ds_read_b128 v[166:169], v117 offset:4672
	s_waitcnt lgkmcnt(5)
	v_sub_f32_e32 v130, v130, v54
	v_sub_f32_e32 v61, v131, v55
	ds_read_b128 v[170:173], v117 offset:4928
	ds_read_b128 v[46:49], v117 offset:5184
	ds_read_b128 v[8:11], v117 offset:5440
	ds_read_b128 v[34:37], v117 offset:5456
	s_waitcnt lgkmcnt(7)
	v_pk_mul_f32 v[54:55], v[130:131], v[162:163]
	v_pk_mul_f32 v[158:159], v[128:129], v[164:165]
	v_sub_f32_e32 v71, v142, v0
	v_sub_f32_e32 v73, v143, v1
	v_sub_f32_e32 v77, v140, v2
	ds_read_b128 v[12:15], v117 offset:5696
	ds_read_b128 v[20:23], v117 offset:5712
	v_sub_f32_e32 v87, v141, v3
	ds_read_b128 v[0:3], v117 offset:5952
	ds_read_b128 v[16:19], v117 offset:5968
	v_add_f32_e32 v131, v54, v55
	v_add_f32_e32 v131, v158, v131
	s_waitcnt lgkmcnt(8)
	v_mov_b32_e32 v206, v168
	v_mov_b32_e32 v207, v166
	ds_read_b128 v[174:177], v117 offset:6208
	ds_read_b128 v[28:31], v117 offset:6224
	ds_read_b128 v[178:181], v117 offset:6464
	ds_read_b128 v[182:185], v117 offset:6480
	v_add_f32_e32 v131, v159, v131
	v_mov_b32_e32 v158, v128
	v_mov_b32_e32 v159, v130
	v_pk_mul_f32 v[158:159], v[158:159], v[206:207]
	v_sub_f32_e32 v131, v61, v131
	s_waitcnt lgkmcnt(9)
	v_mov_b32_e32 v154, v8
	v_mov_b32_e32 v152, v10
	s_waitcnt lgkmcnt(8)
	v_mov_b32_e32 v153, v36
	v_mov_b32_e32 v36, v11
	v_mov_b32_e32 v212, v9
	v_sub_f32_e32 v138, v138, v4
	v_sub_f32_e32 v161, v139, v5
	v_sub_f32_e32 v239, v136, v6
	ds_read_b128 v[24:27], v117 offset:6496
	ds_read_b128 v[186:189], v117 offset:6720
	ds_read_b128 v[190:193], v117 offset:6736
	ds_read_b128 v[8:11], v117 offset:6752
	v_sub_f32_e32 v240, v137, v7
	ds_read_b128 v[194:197], v117 offset:6976
	ds_read_b128 v[4:7], v117 offset:6992
	v_fma_f32 v61, v167, v131, v159
	v_mov_b32_e32 v155, v35
	v_mov_b32_e32 v213, v34
	s_waitcnt lgkmcnt(13)
	v_mov_b32_e32 v74, v14
	s_waitcnt lgkmcnt(12)
	v_mov_b32_e32 v75, v22
	v_mov_b32_e32 v22, v15
	v_mov_b32_e32 v82, v12
	v_mov_b32_e32 v83, v20
	v_mov_b32_e32 v20, v13
	s_waitcnt lgkmcnt(11)
	v_mov_b32_e32 v78, v0
	s_waitcnt lgkmcnt(10)
	v_mov_b32_e32 v79, v16
	v_mov_b32_e32 v16, v1
	v_mov_b32_e32 v118, v2
	v_mov_b32_e32 v119, v18
	v_mov_b32_e32 v18, v3
	ds_read_b128 v[12:15], v117 offset:7008
	ds_read_b128 v[198:201], v117 offset:7232
	ds_read_b128 v[202:205], v117 offset:7248
	ds_read_b128 v[0:3], v117 offset:7264
	ds_read_b128 v[42:45], v117 offset:7488
	ds_read_b128 v[38:41], v117 offset:7504
	ds_read_b128 v[246:249], v117 offset:8000
	ds_read_b128 v[32:35], v117 offset:8016
	ds_read_b128 v[250:253], v117 offset:7744
	ds_read_b128 v[50:53], v117 offset:7760
	v_add_f32_e32 v61, v158, v61
	v_sub_f32_e32 v89, v128, v56
	v_fmac_f32_e32 v61, v129, v169
	s_waitcnt lgkmcnt(14)
	v_mov_b32_e32 v206, v184
	v_mov_b32_e32 v207, v26
	v_mov_b32_e32 v26, v185
	v_pk_mul_f32 v[184:185], v[130:131], v[170:171]
	v_sub_f32_e32 v128, v89, v61
	s_waitcnt lgkmcnt(3)
	v_mov_b32_e32 v84, v248
	s_waitcnt lgkmcnt(2)
	v_mov_b32_e32 v85, v34
	v_mov_b32_e32 v34, v249
	v_pk_mul_f32 v[248:249], v[172:173], v[128:129]
	v_add_f32_e32 v61, v184, v185
	v_mov_b32_e32 v184, v7
	v_add_f32_e32 v7, v61, v248
	v_sub_f32_e32 v69, v129, v57
	v_mov_b32_e32 v185, v15
	v_add_f32_e32 v15, v249, v7
	v_mov_b32_e32 v248, v4
	v_mov_b32_e32 v249, v12
	v_mov_b32_e32 v12, v5
	v_sub_f32_e32 v129, v69, v15
	v_pk_mul_f32 v[4:5], v[130:131], v[46:47]
	v_mov_b32_e32 v7, v14
	v_pk_mul_f32 v[14:15], v[48:49], v[128:129]
	v_add_f32_e32 v4, v4, v5
	v_add_f32_e32 v4, v4, v14
	v_add_f32_e32 v4, v4, v15
	v_sub_f32_e32 v5, v71, v4
	v_mov_b32_e32 v4, v131
	v_mov_b32_e32 v142, v130
	v_pk_mul_f32 v[46:47], v[212:213], v[4:5]
	v_mov_b32_e32 v158, v182
	v_pk_fma_f32 v[46:47], v[142:143], v[154:155], v[46:47]
	v_mov_b32_e32 v142, v128
	v_mov_b32_e32 v143, v140
	v_mov_b32_e32 v182, v183
	v_mov_b32_e32 v159, v25
	v_mov_b32_e32 v183, v24
	v_pk_mul_f32 v[24:25], v[130:131], v[178:179]
	v_pk_fma_f32 v[46:47], v[152:153], v[142:143], v[46:47]
	v_mov_b32_e32 v140, v129
	v_pk_fma_f32 v[36:37], v[36:37], v[140:141], v[46:47]
	v_pk_mul_f32 v[46:47], v[128:129], v[180:181]
	v_add_f32_e32 v24, v24, v25
	v_add_f32_e32 v24, v46, v24
	v_pk_mul_f32 v[14:15], v[130:131], v[186:187]
	v_add_f32_e32 v24, v24, v47
	v_sub_f32_e32 v46, v161, v24
	v_pk_mul_f32 v[24:25], v[128:129], v[188:189]
	v_add_f32_e32 v14, v14, v15
	v_add_f32_e32 v14, v24, v14
	v_pk_mul_f32 v[48:49], v[130:131], v[194:195]
	v_add_f32_e32 v14, v25, v14
	v_sub_f32_e32 v47, v239, v14
	v_pk_mul_f32 v[14:15], v[128:129], v[196:197]
	v_add_f32_e32 v24, v48, v49
	v_add_f32_e32 v14, v14, v24
	v_pk_mul_f32 v[152:153], v[130:131], v[198:199]
	v_add_f32_e32 v14, v15, v14
	v_sub_f32_e32 v48, v240, v14
	v_pk_mul_f32 v[14:15], v[128:129], v[200:201]
	v_add_f32_e32 v24, v152, v153
	v_add_f32_e32 v14, v14, v24
	v_sub_f32_e32 v134, v134, v144
	v_sub_f32_e32 v36, v73, v36
	v_add_f32_e32 v14, v15, v14
	v_sub_f32_e32 v49, v134, v14
	v_sub_f32_e32 v15, v36, v37
	v_mov_b32_e32 v14, v131
	v_mov_b32_e32 v4, v130
	v_pk_mul_f32 v[20:21], v[14:15], v[20:21]
	v_pk_mul_f32 v[16:17], v[14:15], v[16:17]
	v_pk_fma_f32 v[20:21], v[4:5], v[82:83], v[20:21]
	v_pk_fma_f32 v[16:17], v[4:5], v[78:79], v[16:17]
	v_pk_fma_f32 v[20:21], v[74:75], v[142:143], v[20:21]
	v_mov_b32_e32 v215, v28
	v_pk_fma_f32 v[20:21], v[22:23], v[140:141], v[20:21]
	v_mov_b32_e32 v28, v175
	v_sub_f32_e32 v20, v77, v20
	v_sub_f32_e32 v21, v20, v21
	v_mov_b32_e32 v20, v128
	v_pk_fma_f32 v[16:17], v[118:119], v[20:21], v[16:17]
	v_mov_b32_e32 v214, v174
	v_pk_fma_f32 v[16:17], v[18:19], v[140:141], v[16:17]
	v_pk_mul_f32 v[24:25], v[14:15], v[28:29]
	v_mov_b32_e32 v216, v176
	v_mov_b32_e32 v217, v30
	v_sub_f32_e32 v16, v87, v16
	v_pk_fma_f32 v[24:25], v[4:5], v[214:215], v[24:25]
	v_mov_b32_e32 v30, v177
	v_sub_f32_e32 v17, v16, v17
	v_mov_b32_e32 v16, v129
	v_pk_fma_f32 v[24:25], v[216:217], v[20:21], v[24:25]
	v_mov_b32_e32 v78, v15
	v_pk_fma_f32 v[24:25], v[30:31], v[16:17], v[24:25]
	v_mov_b32_e32 v28, v21
	v_sub_f32_e32 v24, v138, v24
	v_sub_f32_e32 v79, v24, v25
	v_mov_b32_e32 v138, v5
	v_pk_mul_f32 v[24:25], v[182:183], v[78:79]
	v_mov_b32_e32 v29, v136
	v_pk_fma_f32 v[24:25], v[158:159], v[138:139], v[24:25]
	v_mov_b32_e32 v136, v17
	v_pk_fma_f32 v[24:25], v[206:207], v[28:29], v[24:25]
	v_mov_b32_e32 v19, v38
	v_mov_b32_e32 v38, v43
	v_pk_fma_f32 v[24:25], v[26:27], v[136:137], v[24:25]
	v_mov_b32_e32 v18, v42
	v_pk_mul_f32 v[22:23], v[14:15], v[38:39]
	v_sub_f32_e32 v24, v46, v24
	v_sub_f32_e32 v220, v133, v147
	v_mov_b32_e32 v147, v8
	v_mov_b32_e32 v8, v191
	v_pk_fma_f32 v[18:19], v[4:5], v[18:19], v[22:23]
	v_mov_b32_e32 v22, v44
	v_mov_b32_e32 v23, v40
	v_sub_f32_e32 v83, v24, v25
	v_mov_b32_e32 v82, v15
	v_sub_f32_e32 v209, v132, v146
	v_mov_b32_e32 v146, v190
	v_pk_fma_f32 v[18:19], v[20:21], v[22:23], v[18:19]
	v_mov_b32_e32 v40, v45
	v_mov_b32_e32 v78, v5
	v_pk_mul_f32 v[8:9], v[8:9], v[82:83]
	v_sub_f32_e32 v241, v135, v145
	v_mov_b32_e32 v144, v192
	v_mov_b32_e32 v145, v10
	v_pk_fma_f32 v[18:19], v[16:17], v[40:41], v[18:19]
	v_pk_fma_f32 v[8:9], v[146:147], v[78:79], v[8:9]
	v_mov_b32_e32 v81, v32
	v_mov_b32_e32 v32, v247
	v_mov_b32_e32 v10, v193
	v_sub_f32_e32 v18, v241, v18
	v_pk_fma_f32 v[8:9], v[144:145], v[28:29], v[8:9]
	v_mov_b32_e32 v80, v246
	v_sub_f32_e32 v26, v18, v19
	v_pk_mul_f32 v[18:19], v[14:15], v[32:33]
	v_pk_fma_f32 v[8:9], v[10:11], v[136:137], v[8:9]
	v_pk_fma_f32 v[18:19], v[4:5], v[80:81], v[18:19]
	v_sub_f32_e32 v8, v47, v8
	v_pk_fma_f32 v[18:19], v[20:21], v[84:85], v[18:19]
	v_sub_f32_e32 v85, v8, v9
	v_pk_mul_f32 v[8:9], v[12:13], v[82:83]
	v_mov_b32_e32 v84, v21
	v_pk_fma_f32 v[8:9], v[78:79], v[248:249], v[8:9]
	v_mov_b32_e32 v219, v0
	v_mov_b32_e32 v0, v203
	v_pk_fma_f32 v[6:7], v[6:7], v[84:85], v[8:9]
	v_mov_b32_e32 v218, v202
	ds_read_b128 v[174:177], v117 offset:7520
	ds_read_b128 v[190:193], v117 offset:7536
	v_pk_fma_f32 v[6:7], v[184:185], v[136:137], v[6:7]
	v_pk_mul_f32 v[0:1], v[0:1], v[82:83]
	v_mov_b32_e32 v202, v204
	v_mov_b32_e32 v203, v2
	v_sub_f32_e32 v6, v48, v6
	v_pk_fma_f32 v[0:1], v[78:79], v[218:219], v[0:1]
	v_mov_b32_e32 v2, v205
	v_sub_f32_e32 v75, v6, v7
	v_pk_fma_f32 v[0:1], v[202:203], v[84:85], v[0:1]
	v_mov_b32_e32 v74, v17
	v_pk_fma_f32 v[0:1], v[2:3], v[74:75], v[0:1]
	s_waitcnt lgkmcnt(1)
	v_mov_b32_e32 v8, v175
	v_sub_f32_e32 v0, v49, v0
	v_sub_f32_e32 v81, v0, v1
	s_waitcnt lgkmcnt(0)
	v_mov_b32_e32 v9, v190
	v_mov_b32_e32 v80, v83
	ds_read_b128 v[162:165], v117 offset:7776
	ds_read_b128 v[54:57], v117 offset:7792
	v_mov_b32_e32 v0, v174
	v_mov_b32_e32 v1, v191
	v_mov_b32_e32 v134, v79
	v_pk_mul_f32 v[8:9], v[8:9], v[80:81]
	v_mov_b32_e32 v2, v176
	v_mov_b32_e32 v3, v192
	v_mov_b32_e32 v6, v85
	v_mov_b32_e32 v7, v132
	v_pk_fma_f32 v[0:1], v[0:1], v[134:135], v[8:9]
	v_mov_b32_e32 v192, v177
	v_mov_b32_e32 v132, v75
	v_pk_fma_f32 v[0:1], v[2:3], v[6:7], v[0:1]
	v_mov_b32_e32 v205, v50
	v_mov_b32_e32 v50, v251
	v_pk_fma_f32 v[0:1], v[192:193], v[132:133], v[0:1]
	v_mov_b32_e32 v204, v250
	v_pk_mul_f32 v[22:23], v[14:15], v[50:51]
	v_sub_f32_e32 v0, v26, v0
	v_mov_b32_e32 v246, v252
	v_mov_b32_e32 v247, v52
	v_pk_fma_f32 v[22:23], v[4:5], v[204:205], v[22:23]
	v_sub_f32_e32 v119, v0, v1
	s_waitcnt lgkmcnt(0)
	v_mov_b32_e32 v3, v54
	v_mov_b32_e32 v54, v163
	v_mov_b32_e32 v118, v83
	v_mov_b32_e32 v52, v253
	ds_read_b128 v[166:169], v117 offset:8032
	ds_read_b128 v[170:173], v117 offset:8048
	v_pk_fma_f32 v[22:23], v[20:21], v[246:247], v[22:23]
	v_mov_b32_e32 v2, v162
	v_mov_b32_e32 v80, v79
	v_pk_mul_f32 v[8:9], v[54:55], v[118:119]
	v_pk_fma_f32 v[22:23], v[16:17], v[52:53], v[22:23]
	v_mov_b32_e32 v0, v164
	v_mov_b32_e32 v1, v56
	v_pk_fma_f32 v[2:3], v[2:3], v[80:81], v[8:9]
	v_sub_f32_e32 v22, v209, v22
	v_mov_b32_e32 v56, v165
	v_pk_fma_f32 v[0:1], v[0:1], v[6:7], v[2:3]
	v_sub_f32_e32 v22, v22, v23
	v_pk_fma_f32 v[0:1], v[56:57], v[132:133], v[0:1]
	v_pk_fma_f32 v[18:19], v[16:17], v[34:35], v[18:19]
	v_sub_f32_e32 v0, v22, v0
	v_sub_f32_e32 v135, v0, v1
	s_waitcnt lgkmcnt(0)
	v_mov_b32_e32 v1, v170
	v_mov_b32_e32 v170, v167
	v_mov_b32_e32 v0, v166
	v_pk_mul_f32 v[2:3], v[170:171], v[118:119]
	v_mov_b32_e32 v134, v85
	v_pk_fma_f32 v[0:1], v[0:1], v[80:81], v[2:3]
	v_mov_b32_e32 v2, v168
	v_mov_b32_e32 v3, v172
	v_sub_f32_e32 v4, v220, v18
	v_pk_fma_f32 v[0:1], v[2:3], v[134:135], v[0:1]
	v_mov_b32_e32 v172, v169
	v_sub_f32_e32 v4, v4, v19
	v_pk_fma_f32 v[0:1], v[172:173], v[132:133], v[0:1]
	v_cvt_pk_bf16_f32 v2, v5, v15
	v_sub_f32_e32 v0, v4, v0
	v_sub_f32_e32 v146, v0, v1
	v_cvt_pk_bf16_f32 v0, v130, v131
	v_cvt_pk_bf16_f32 v1, v128, v129
	v_cvt_pk_bf16_f32 v3, v21, v17
	ds_write_b128 v160, v[0:3] offset:32800
	v_cvt_pk_bf16_f32 v0, v79, v83
	v_cvt_pk_bf16_f32 v1, v85, v75
	v_cvt_pk_bf16_f32 v2, v81, v119
	v_cvt_pk_bf16_f32 v3, v135, v146
	ds_write_b128 v160, v[0:3] offset:32816
	s_waitcnt lgkmcnt(0)
	ds_read_b128 v[0:3], v157 offset:8192
	ds_read_b128 v[6:9], v157 offset:8208
	v_cvt_pk_bf16_f32 v138, v5, s0
	v_cvt_pk_bf16_f32 v144, v150, s0
	v_cvt_pk_bf16_f32 v139, v15, s0
	s_waitcnt lgkmcnt(1)
	v_cvt_pk_bf16_f32 v0, v0, v1
	v_cvt_pk_bf16_f32 v1, v2, v3
	s_waitcnt lgkmcnt(0)
	v_cvt_pk_bf16_f32 v2, v6, v7
	v_cvt_pk_bf16_f32 v3, v8, v9
	ds_read_b128 v[6:9], v64 offset:32768
	v_cvt_pk_bf16_f32 v74, v58, s0
	s_waitcnt lgkmcnt(0)
	v_mfma_f32_16x16x32_bf16 v[6:9], v[0:3], v[6:9], 0
	v_cvt_pk_bf16_f32 v78, v68, s0
	v_cvt_pk_bf16_f32 v80, v72, s0
	v_cvt_pk_bf16_f32 v133, v60, s0
	s_nop 4
	ds_write_b128 v151, v[6:9] offset:16384
	ds_read_b128 v[6:9], v64 offset:35072
	s_waitcnt lgkmcnt(0)
	v_mfma_f32_16x16x32_bf16 v[6:9], v[0:3], v[6:9], 0
	v_cvt_pk_bf16_f32 v136, v76, s0
	v_cvt_pk_bf16_f32 v142, v88, s0
	v_cvt_pk_bf16_f32 v145, v59, s0
	s_nop 4
	ds_write_b128 v151, v[6:9] offset:17408
	ds_read_b128 v[6:9], v64 offset:37376
	s_waitcnt lgkmcnt(0)
	v_mfma_f32_16x16x32_bf16 v[6:9], v[0:3], v[6:9], 0
	v_cvt_pk_bf16_f32 v82, v130, s0
	v_cvt_pk_bf16_f32 v84, v131, s0
	v_cvt_pk_bf16_f32 v140, v21, s0
	s_nop 4
	ds_write_b128 v151, v[6:9] offset:18432
	ds_read_b128 v[6:9], v66 offset:32768
	s_waitcnt lgkmcnt(0)
	v_mfma_f32_16x16x32_bf16 v[0:3], v[0:3], v[6:9], 0
	v_cvt_pk_bf16_f32 v141, v17, s0
	v_cvt_pk_bf16_f32 v137, v86, s0
	v_cvt_pk_bf16_f32 v143, v148, s0
	s_nop 4
	ds_write_b128 v156, v[0:3] offset:16384
	s_waitcnt lgkmcnt(0)
	ds_read_b128 v[152:155], v62 offset:16384
	ds_read_b128 v[0:3], v62 offset:16400
	ds_read_b128 v[162:165], v117 offset:8576
	ds_read_b128 v[4:7], v62 offset:16416
	ds_read_b128 v[166:169], v62 offset:16432
	ds_read_b128 v[170:173], v117 offset:8832
	s_waitcnt lgkmcnt(4)
	v_sub_f32_e32 v150, v126, v0
	ds_read_b128 v[174:177], v117 offset:9088
	ds_read_b128 v[54:57], v117 offset:9344
	v_sub_f32_e32 v161, v127, v1
	ds_read_b128 v[8:11], v117 offset:9600
	ds_read_b128 v[42:45], v117 offset:9616
	v_sub_f32_e32 v209, v124, v2
	ds_read_b128 v[12:15], v117 offset:9856
	ds_read_b128 v[28:31], v117 offset:9872
	v_sub_f32_e32 v220, v125, v3
	ds_read_b128 v[0:3], v117 offset:10112
	ds_read_b128 v[24:27], v117 offset:10128
	s_waitcnt lgkmcnt(11)
	v_pk_mul_f32 v[158:159], v[98:99], v[164:165]
	s_waitcnt lgkmcnt(5)
	v_mov_b32_e32 v212, v8
	s_waitcnt lgkmcnt(4)
	v_mov_b32_e32 v213, v43
	v_mov_b32_e32 v130, v10
	v_mov_b32_e32 v131, v44
	v_mov_b32_e32 v44, v11
	v_mov_b32_e32 v214, v9
	v_mov_b32_e32 v215, v42
	s_waitcnt lgkmcnt(3)
	v_mov_b32_e32 v68, v14
	s_waitcnt lgkmcnt(2)
	v_mov_b32_e32 v69, v30
	v_mov_b32_e32 v30, v15
	v_mov_b32_e32 v76, v12
	v_mov_b32_e32 v77, v28
	v_mov_b32_e32 v28, v13
	s_waitcnt lgkmcnt(1)
	v_mov_b32_e32 v72, v0
	s_waitcnt lgkmcnt(0)
	v_mov_b32_e32 v73, v24
	v_mov_b32_e32 v24, v1
	v_mov_b32_e32 v88, v2
	v_mov_b32_e32 v89, v26
	v_mov_b32_e32 v26, v3
	v_sub_f32_e32 v122, v122, v4
	ds_read_b128 v[178:181], v117 offset:10368
	ds_read_b128 v[36:39], v117 offset:10384
	v_sub_f32_e32 v239, v123, v5
	ds_read_b128 v[182:185], v117 offset:10624
	ds_read_b128 v[186:189], v117 offset:10640
	v_sub_f32_e32 v240, v120, v6
	ds_read_b128 v[32:35], v117 offset:10656
	ds_read_b128 v[190:193], v117 offset:10880
	ds_read_b128 v[194:197], v117 offset:10896
	ds_read_b128 v[16:19], v117 offset:10912
	v_sub_f32_e32 v241, v121, v7
	ds_read_b128 v[198:201], v117 offset:11136
	ds_read_b128 v[12:15], v117 offset:11152
	v_sub_f32_e32 v114, v114, v166
	ds_read_b128 v[20:23], v117 offset:11168
	ds_read_b128 v[202:205], v117 offset:11392
	ds_read_b128 v[246:249], v117 offset:11408
	ds_read_b128 v[8:11], v117 offset:11424
	v_sub_f32_e32 v221, v115, v167
	ds_read_b128 v[50:53], v117 offset:11648
	ds_read_b128 v[46:49], v117 offset:11664
	ds_read_b128 v[4:7], v117 offset:11680
	ds_read_b128 v[0:3], v117 offset:11696
	ds_read_b128 v[164:167], v117 offset:12160
	ds_read_b128 v[40:43], v117 offset:12176
	ds_read_b128 v[250:253], v117 offset:11904
	ds_read_b128 v[58:61], v117 offset:11920
	v_sub_f32_e32 v100, v100, v152
	s_waitcnt lgkmcnt(3)
	v_mov_b32_e32 v86, v166
	s_waitcnt lgkmcnt(2)
	v_mov_b32_e32 v87, v42
	v_mov_b32_e32 v42, v167
	v_pk_mul_f32 v[166:167], v[100:101], v[162:163]
	v_sub_f32_e32 v147, v101, v153
	v_add_f32_e32 v101, v166, v167
	v_add_f32_e32 v101, v158, v101
	v_mov_b32_e32 v206, v172
	v_mov_b32_e32 v207, v170
	v_add_f32_e32 v101, v159, v101
	v_mov_b32_e32 v158, v98
	v_mov_b32_e32 v159, v100
	v_pk_mul_f32 v[158:159], v[158:159], v[206:207]
	v_sub_f32_e32 v101, v147, v101
	v_sub_f32_e32 v126, v98, v154
	v_fma_f32 v98, v171, v101, v159
	v_add_f32_e32 v98, v158, v98
	v_fmac_f32_e32 v98, v99, v173
	v_sub_f32_e32 v98, v126, v98
	v_pk_mul_f32 v[174:175], v[100:101], v[174:175]
	v_pk_mul_f32 v[176:177], v[176:177], v[98:99]
	v_mov_b32_e32 v206, v12
	v_add_f32_e32 v12, v174, v175
	v_add_f32_e32 v12, v12, v176
	v_sub_f32_e32 v148, v99, v155
	v_mov_b32_e32 v158, v15
	v_mov_b32_e32 v15, v22
	v_add_f32_e32 v22, v177, v12
	v_mov_b32_e32 v207, v20
	v_mov_b32_e32 v20, v13
	v_pk_mul_f32 v[12:13], v[100:101], v[54:55]
	v_sub_f32_e32 v99, v148, v22
	v_mov_b32_e32 v216, v248
	v_mov_b32_e32 v217, v10
	v_mov_b32_e32 v10, v249
	v_mov_b32_e32 v248, v188
	v_mov_b32_e32 v249, v34
	v_mov_b32_e32 v34, v189
	v_mov_b32_e32 v188, v187
	v_mov_b32_e32 v187, v33
	v_mov_b32_e32 v189, v32
	v_pk_mul_f32 v[32:33], v[56:57], v[98:99]
	v_add_f32_e32 v12, v12, v13
	v_add_f32_e32 v12, v12, v32
	v_add_f32_e32 v12, v12, v33
	v_sub_f32_e32 v13, v150, v12
	v_mov_b32_e32 v12, v101
	v_mov_b32_e32 v126, v100
	v_pk_mul_f32 v[174:175], v[214:215], v[12:13]
	v_mov_b32_e32 v159, v23
	v_pk_fma_f32 v[126:127], v[126:127], v[212:213], v[174:175]
	v_mov_b32_e32 v174, v98
	v_mov_b32_e32 v175, v124
	v_pk_mul_f32 v[22:23], v[100:101], v[182:183]
	v_mov_b32_e32 v124, v99
	v_pk_fma_f32 v[126:127], v[130:131], v[174:175], v[126:127]
	v_add_f32_e32 v22, v22, v23
	v_pk_fma_f32 v[44:45], v[44:45], v[124:125], v[126:127]
	v_pk_mul_f32 v[126:127], v[98:99], v[184:185]
	v_pk_mul_f32 v[54:55], v[100:101], v[190:191]
	v_add_f32_e32 v22, v126, v22
	v_add_f32_e32 v22, v22, v127
	v_sub_f32_e32 v126, v239, v22
	v_pk_mul_f32 v[22:23], v[98:99], v[192:193]
	v_add_f32_e32 v54, v54, v55
	v_add_f32_e32 v22, v22, v54
	v_pk_mul_f32 v[56:57], v[100:101], v[198:199]
	v_add_f32_e32 v22, v23, v22
	v_sub_f32_e32 v54, v240, v22
	v_pk_mul_f32 v[22:23], v[98:99], v[200:201]
	v_add_f32_e32 v55, v56, v57
	v_add_f32_e32 v22, v22, v55
	v_pk_mul_f32 v[32:33], v[100:101], v[202:203]
	v_add_f32_e32 v22, v23, v22
	v_sub_f32_e32 v55, v241, v22
	v_pk_mul_f32 v[22:23], v[98:99], v[204:205]
	v_add_f32_e32 v32, v32, v33
	v_add_f32_e32 v22, v22, v32
	v_sub_f32_e32 v44, v161, v44
	v_add_f32_e32 v22, v23, v22
	v_sub_f32_e32 v56, v114, v22
	v_sub_f32_e32 v23, v44, v45
	v_mov_b32_e32 v22, v101
	v_mov_b32_e32 v12, v100
	v_pk_mul_f32 v[28:29], v[22:23], v[28:29]
	v_pk_mul_f32 v[24:25], v[22:23], v[24:25]
	v_pk_fma_f32 v[28:29], v[12:13], v[76:77], v[28:29]
	v_pk_fma_f32 v[24:25], v[12:13], v[72:73], v[24:25]
	v_pk_fma_f32 v[28:29], v[68:69], v[174:175], v[28:29]
	v_cvt_pk_bf16_f32 v132, v129, s0
	v_pk_fma_f32 v[28:29], v[30:31], v[124:125], v[28:29]
	v_mov_b32_e32 v129, v18
	v_sub_f32_e32 v28, v209, v28
	v_sub_f32_e32 v29, v28, v29
	v_mov_b32_e32 v28, v98
	v_mov_b32_e32 v18, v197
	v_mov_b32_e32 v197, v16
	v_mov_b32_e32 v16, v195
	v_mov_b32_e32 v195, v36
	v_mov_b32_e32 v36, v179
	v_pk_fma_f32 v[24:25], v[88:89], v[28:29], v[24:25]
	v_cvt_pk_bf16_f32 v118, v128, s0
	v_mov_b32_e32 v128, v196
	v_mov_b32_e32 v196, v194
	v_mov_b32_e32 v194, v178
	v_pk_fma_f32 v[24:25], v[26:27], v[124:125], v[24:25]
	v_pk_mul_f32 v[32:33], v[22:23], v[36:37]
	v_mov_b32_e32 v178, v180
	v_mov_b32_e32 v179, v38
	v_sub_f32_e32 v24, v220, v24
	v_pk_fma_f32 v[32:33], v[12:13], v[194:195], v[32:33]
	v_mov_b32_e32 v38, v181
	v_sub_f32_e32 v25, v24, v25
	v_mov_b32_e32 v24, v99
	v_pk_fma_f32 v[32:33], v[178:179], v[28:29], v[32:33]
	v_mov_b32_e32 v27, v46
	v_mov_b32_e32 v46, v51
	v_pk_fma_f32 v[32:33], v[38:39], v[24:25], v[32:33]
	v_mov_b32_e32 v26, v50
	v_pk_mul_f32 v[30:31], v[22:23], v[46:47]
	v_sub_f32_e32 v32, v122, v32
	v_pk_fma_f32 v[26:27], v[12:13], v[26:27], v[30:31]
	v_mov_b32_e32 v30, v52
	v_mov_b32_e32 v31, v48
	v_sub_f32_e32 v33, v32, v33
	v_mov_b32_e32 v32, v23
	v_pk_fma_f32 v[26:27], v[28:29], v[30:31], v[26:27]
	v_mov_b32_e32 v48, v53
	v_mov_b32_e32 v122, v13
	v_pk_mul_f32 v[38:39], v[188:189], v[32:33]
	v_pk_fma_f32 v[26:27], v[24:25], v[48:49], v[26:27]
	v_mov_b32_e32 v36, v29
	v_mov_b32_e32 v37, v120
	v_pk_fma_f32 v[38:39], v[186:187], v[122:123], v[38:39]
	v_mov_b32_e32 v71, v40
	v_mov_b32_e32 v40, v165
	v_sub_f32_e32 v26, v221, v26
	v_mov_b32_e32 v120, v25
	v_pk_fma_f32 v[38:39], v[248:249], v[36:37], v[38:39]
	v_cvt_pk_bf16_f32 v134, v70, s0
	v_mov_b32_e32 v70, v164
	v_pk_fma_f32 v[34:35], v[34:35], v[120:121], v[38:39]
	v_sub_f32_e32 v38, v26, v27
	v_pk_mul_f32 v[26:27], v[22:23], v[40:41]
	s_waitcnt lgkmcnt(0)
	v_mov_b32_e32 v219, v58
	v_pk_fma_f32 v[26:27], v[12:13], v[70:71], v[26:27]
	v_mov_b32_e32 v58, v251
	v_pk_fma_f32 v[26:27], v[28:29], v[86:87], v[26:27]
	v_sub_f32_e32 v223, v113, v169
	v_mov_b32_e32 v218, v250
	v_pk_mul_f32 v[30:31], v[22:23], v[58:59]
	v_pk_fma_f32 v[26:27], v[24:25], v[42:43], v[26:27]
	v_pk_fma_f32 v[30:31], v[12:13], v[218:219], v[30:31]
	v_sub_f32_e32 v34, v126, v34
	v_sub_f32_e32 v12, v223, v26
	v_sub_f32_e32 v12, v12, v27
	v_sub_f32_e32 v27, v34, v35
	v_mov_b32_e32 v26, v23
	v_mov_b32_e32 v32, v13
	v_pk_mul_f32 v[16:17], v[16:17], v[26:27]
	v_mov_b32_e32 v181, v8
	v_pk_fma_f32 v[16:17], v[196:197], v[32:33], v[16:17]
	v_mov_b32_e32 v8, v247
	v_pk_fma_f32 v[16:17], v[128:129], v[36:37], v[16:17]
	v_mov_b32_e32 v180, v246
	v_pk_fma_f32 v[16:17], v[18:19], v[120:121], v[16:17]
	v_mov_b32_e32 v18, v29
	v_sub_f32_e32 v16, v54, v16
	v_sub_f32_e32 v19, v16, v17
	v_pk_mul_f32 v[16:17], v[20:21], v[26:27]
	v_pk_mul_f32 v[8:9], v[8:9], v[26:27]
	v_pk_fma_f32 v[16:17], v[32:33], v[206:207], v[16:17]
	v_mov_b32_e32 v246, v252
	v_pk_fma_f32 v[14:15], v[14:15], v[18:19], v[16:17]
	v_mov_b32_e32 v247, v60
	v_pk_fma_f32 v[14:15], v[158:159], v[120:121], v[14:15]
	v_pk_fma_f32 v[8:9], v[32:33], v[180:181], v[8:9]
	v_sub_f32_e32 v14, v55, v14
	v_mov_b32_e32 v60, v253
	v_pk_fma_f32 v[30:31], v[28:29], v[246:247], v[30:31]
	v_sub_f32_e32 v21, v14, v15
	v_pk_fma_f32 v[8:9], v[216:217], v[18:19], v[8:9]
	v_mov_b32_e32 v20, v25
	v_sub_f32_e32 v222, v112, v168
	v_pk_fma_f32 v[30:31], v[24:25], v[60:61], v[30:31]
	v_pk_fma_f32 v[8:9], v[10:11], v[20:21], v[8:9]
	v_sub_f32_e32 v30, v222, v30
	v_sub_f32_e32 v8, v56, v8
	v_sub_f32_e32 v39, v30, v31
	v_sub_f32_e32 v31, v8, v9
	v_mov_b32_e32 v8, v4
	v_mov_b32_e32 v4, v5
	v_mov_b32_e32 v5, v0
	v_mov_b32_e32 v30, v27
	ds_read_b128 v[152:155], v117 offset:11936
	ds_read_b128 v[162:165], v117 offset:11952
	v_mov_b32_e32 v9, v1
	v_mov_b32_e32 v114, v33
	v_pk_mul_f32 v[0:1], v[4:5], v[30:31]
	v_mov_b32_e32 v10, v6
	v_mov_b32_e32 v11, v2
	v_mov_b32_e32 v14, v19
	v_mov_b32_e32 v15, v112
	v_pk_fma_f32 v[0:1], v[8:9], v[114:115], v[0:1]
	v_mov_b32_e32 v2, v7
	v_mov_b32_e32 v112, v21
	v_pk_fma_f32 v[0:1], v[10:11], v[14:15], v[0:1]
	v_mov_b32_e32 v34, v27
	v_pk_fma_f32 v[0:1], v[2:3], v[112:113], v[0:1]
	s_waitcnt lgkmcnt(0)
	v_mov_b32_e32 v3, v162
	v_sub_f32_e32 v0, v38, v0
	v_sub_f32_e32 v35, v0, v1
	v_mov_b32_e32 v162, v153
	ds_read_b128 v[166:169], v117 offset:12192
	ds_read_b128 v[170:173], v117 offset:12208
	v_mov_b32_e32 v2, v152
	v_mov_b32_e32 v30, v33
	v_pk_mul_f32 v[4:5], v[162:163], v[34:35]
	v_mov_b32_e32 v0, v154
	v_mov_b32_e32 v1, v164
	v_pk_fma_f32 v[2:3], v[2:3], v[30:31], v[4:5]
	v_mov_b32_e32 v164, v155
	v_pk_fma_f32 v[0:1], v[0:1], v[14:15], v[2:3]
	v_mov_b32_e32 v36, v19
	v_pk_fma_f32 v[0:1], v[164:165], v[112:113], v[0:1]
	v_cvt_pk_bf16_f32 v77, v135, s0
	v_sub_f32_e32 v0, v39, v0
	v_sub_f32_e32 v37, v0, v1
	s_waitcnt lgkmcnt(0)
	v_mov_b32_e32 v1, v170
	v_mov_b32_e32 v170, v167
	v_mov_b32_e32 v0, v166
	v_pk_mul_f32 v[2:3], v[170:171], v[34:35]
	v_cvt_pk_bf16_f32 v135, v13, s0
	v_pk_fma_f32 v[0:1], v[0:1], v[30:31], v[2:3]
	v_mov_b32_e32 v2, v168
	v_mov_b32_e32 v3, v172
	v_pk_fma_f32 v[0:1], v[2:3], v[36:37], v[0:1]
	v_mov_b32_e32 v172, v169
	v_pk_fma_f32 v[0:1], v[172:173], v[112:113], v[0:1]
	v_cvt_pk_bf16_f32 v2, v13, v23
	v_sub_f32_e32 v0, v12, v0
	v_sub_f32_e32 v18, v0, v1
	v_cvt_pk_bf16_f32 v0, v100, v101
	v_cvt_pk_bf16_f32 v1, v98, v99
	v_cvt_pk_bf16_f32 v3, v29, v25
	ds_write_b128 v160, v[0:3] offset:32832
	v_cvt_pk_bf16_f32 v0, v33, v27
	v_cvt_pk_bf16_f32 v1, v19, v21
	v_cvt_pk_bf16_f32 v2, v31, v35
	v_cvt_pk_bf16_f32 v3, v37, v18
	ds_write_b128 v160, v[0:3] offset:32848
	s_waitcnt lgkmcnt(0)
	ds_read_b128 v[0:3], v157 offset:12288
	ds_read_b128 v[4:7], v157 offset:12304
	ds_read_b128 v[8:11], v157 offset:12416
	v_or_b32_e32 v12, 32, v116
	v_cmp_gt_u32_e64 s[4:5], 48, v12
	s_waitcnt lgkmcnt(2)
	v_cvt_pk_bf16_f32 v0, v0, v1
	v_cvt_pk_bf16_f32 v1, v2, v3
	s_waitcnt lgkmcnt(1)
	v_cvt_pk_bf16_f32 v2, v4, v5
	v_cvt_pk_bf16_f32 v3, v6, v7
	ds_read_b128 v[4:7], v157 offset:12432
	s_waitcnt lgkmcnt(1)
	v_cndmask_b32_e64 v9, 0, v9, s[4:5]
	v_cndmask_b32_e64 v8, 0, v8, s[4:5]
	v_cndmask_b32_e64 v12, 0, v11, s[4:5]
	v_cndmask_b32_e64 v14, 0, v10, s[4:5]
	s_waitcnt lgkmcnt(0)
	v_cndmask_b32_e64 v16, 0, v4, s[4:5]
	v_cvt_pk_bf16_f32 v4, v8, v9
	ds_read_b128 v[8:11], v64 offset:32768
	v_cndmask_b32_e64 v7, 0, v7, s[4:5]
	v_cndmask_b32_e64 v15, 0, v6, s[4:5]
	v_cndmask_b32_e64 v6, 0, v5, s[4:5]
	v_cvt_pk_bf16_f32 v5, v14, v12
	v_cvt_pk_bf16_f32 v6, v16, v6
	v_cvt_pk_bf16_f32 v7, v15, v7
	ds_read_b128 v[14:17], v64 offset:32832
	s_waitcnt lgkmcnt(1)
	v_mfma_f32_16x16x32_bf16 v[8:11], v[0:3], v[8:11], 0
	v_cvt_pk_bf16_f32 v60, v79, s0
	v_cvt_pk_bf16_f32 v61, v83, s0
	v_cvt_pk_bf16_f32 v72, v85, s0
	s_waitcnt lgkmcnt(0)
	v_mfma_f32_16x16x32_bf16 v[8:11], v[4:7], v[14:17], v[8:11]
	v_cvt_pk_bf16_f32 v73, v75, s0
	v_cvt_pk_bf16_f32 v75, v81, s0
	v_cvt_pk_bf16_f32 v76, v119, s0
	v_cvt_pk_bf16_f32 v79, v146, s0
	v_cvt_pk_bf16_f32 v81, v100, s0
	s_nop 2
	ds_write_b128 v151, v[8:11] offset:16384
	ds_read_b128 v[8:11], v64 offset:35072
	ds_read_b128 v[14:17], v64 offset:35136
	s_waitcnt lgkmcnt(1)
	v_mfma_f32_16x16x32_bf16 v[8:11], v[0:3], v[8:11], 0
	v_cvt_pk_bf16_f32 v83, v101, s0
	v_cvt_pk_bf16_f32 v85, v98, s0
	v_cvt_pk_bf16_f32 v119, v99, s0
	s_waitcnt lgkmcnt(0)
	v_mfma_f32_16x16x32_bf16 v[8:11], v[4:7], v[14:17], v[8:11]
	v_cvt_pk_bf16_f32 v146, v23, s0
	v_cvt_pk_bf16_f32 v147, v29, s0
	v_cvt_pk_bf16_f32 v148, v33, s0
	v_cvt_pk_bf16_f32 v206, v27, s0
	v_cvt_pk_bf16_f32 v207, v19, s0
	s_nop 2
	ds_write_b128 v151, v[8:11] offset:17408
	ds_read_b128 v[8:11], v64 offset:37376
	ds_read_b128 v[12:15], v64 offset:37440
	s_waitcnt lgkmcnt(1)
	v_mfma_f32_16x16x32_bf16 v[8:11], v[0:3], v[8:11], 0
	v_cvt_pk_bf16_f32 v64, v25, s0
	v_cvt_pk_bf16_f32 v209, v21, s0
	v_cvt_pk_bf16_f32 v220, v31, s0
	s_waitcnt lgkmcnt(0)
	v_mfma_f32_16x16x32_bf16 v[8:11], v[4:7], v[12:15], v[8:11]
	v_cvt_pk_bf16_f32 v221, v37, s0
	v_cvt_pk_bf16_f32 v222, v18, s0
	s_cmpk_gt_i32 s46, 0xfff
	s_nop 4
	ds_write_b128 v151, v[8:11] offset:18432
	ds_read_b128 v[8:11], v66 offset:32768
	ds_read_b128 v[12:15], v66 offset:32832
	s_waitcnt lgkmcnt(1)
	v_mfma_f32_16x16x32_bf16 v[0:3], v[0:3], v[8:11], 0
	v_cvt_pk_bf16_f32 v66, v35, s0
	s_waitcnt lgkmcnt(0)
	v_mfma_f32_16x16x32_bf16 v[0:3], v[4:7], v[12:15], v[0:3]
	s_nop 7
	ds_write_b128 v156, v[0:3] offset:16384
	s_waitcnt lgkmcnt(0)
	ds_read_b128 v[36:39], v62 offset:16384
	ds_read_b128 v[40:43], v62 offset:16400
	ds_read_b128 v[44:47], v62 offset:16416
	ds_read_b128 v[0:3], v62 offset:16432
	ds_read_b128 v[48:51], v117 offset:12736
	ds_read_b128 v[52:55], v117 offset:12992
	ds_read_b128 v[56:59], v117 offset:13248
	ds_read_b128 v[68:71], v117 offset:13504
	ds_read_b128 v[86:89], v117 offset:13760
	ds_read_b128 v[98:101], v117 offset:13776
	ds_read_b128 v[112:115], v117 offset:14016
	ds_read_b128 v[120:123], v117 offset:14032
	ds_read_b128 v[124:127], v117 offset:14272
	ds_read_b128 v[128:131], v117 offset:14288
	ds_read_b128 v[150:153], v117 offset:14528
	ds_read_b128 v[154:157], v117 offset:14544
	ds_read_b128 v[158:161], v117 offset:14784
	ds_read_b128 v[162:165], v117 offset:14800
	ds_read_b128 v[166:169], v117 offset:14816
	ds_read_b128 v[170:173], v117 offset:15040
	ds_read_b128 v[174:177], v117 offset:15056
	ds_read_b128 v[178:181], v117 offset:15072
	ds_read_b128 v[182:185], v117 offset:15296
	ds_read_b128 v[186:189], v117 offset:15312
	ds_read_b128 v[190:193], v117 offset:15328
	ds_read_b128 v[194:197], v117 offset:15552
	ds_read_b128 v[198:201], v117 offset:15568
	ds_read_b128 v[202:205], v117 offset:15584
	ds_read_b128 v[246:249], v117 offset:15808
	ds_read_b128 v[32:35], v117 offset:15824
	ds_read_b128 v[28:31], v117 offset:15840
	ds_read_b128 v[24:27], v117 offset:15856
	ds_read_b128 v[20:23], v117 offset:16064
	ds_read_b128 v[16:19], v117 offset:16080
	ds_read_b128 v[12:15], v117 offset:16096
	ds_read_b128 v[8:11], v117 offset:16112
	ds_read_b128 v[250:253], v117 offset:16320
	ds_read_b128 v[212:215], v117 offset:16336
	ds_read_b128 v[216:219], v117 offset:16352
	ds_read_b128 v[4:7], v117 offset:16368
	s_waitcnt lgkmcnt(14)
	v_sub_f32_e32 v36, v110, v36
	v_mul_f32_e32 v49, v111, v49
	v_fmac_f32_e32 v49, v36, v48
	v_fmac_f32_e32 v49, v108, v50
	v_sub_f32_e32 v37, v111, v37
	v_fmac_f32_e32 v49, v109, v51
	v_sub_f32_e32 v37, v37, v49
	v_mul_f32_e32 v49, v53, v37
	v_fmac_f32_e32 v49, v36, v52
	v_fmac_f32_e32 v49, v108, v54
	v_sub_f32_e32 v38, v108, v38
	v_fmac_f32_e32 v49, v109, v55
	v_sub_f32_e32 v38, v38, v49
	v_mul_f32_e32 v49, v57, v37
	v_fmac_f32_e32 v49, v36, v56
	s_waitcnt lgkmcnt(3)
	v_mul_f32_e32 v48, v37, v251
	v_fmac_f32_e32 v49, v58, v38
	v_fmac_f32_e32 v48, v36, v250
	v_sub_f32_e32 v39, v109, v39
	v_fmac_f32_e32 v49, v109, v59
	v_fmac_f32_e32 v48, v38, v252
	v_sub_f32_e32 v39, v39, v49
	v_sub_f32_e32 v3, v93, v3
	v_fmac_f32_e32 v48, v39, v253
	v_sub_f32_e32 v3, v3, v48
	v_mul_f32_e32 v48, v69, v37
	v_fmac_f32_e32 v48, v36, v68
	v_fmac_f32_e32 v48, v70, v38
	v_sub_f32_e32 v40, v106, v40
	v_fmac_f32_e32 v48, v71, v39
	v_sub_f32_e32 v40, v40, v48
	v_mul_f32_e32 v48, v87, v37
	v_fmac_f32_e32 v48, v36, v86
	v_fmac_f32_e32 v48, v88, v38
	v_sub_f32_e32 v41, v107, v41
	v_fmac_f32_e32 v48, v89, v39
	v_sub_f32_e32 v41, v41, v48
	v_mul_f32_e32 v48, v98, v40
	v_fmac_f32_e32 v48, v107, v99
	v_mul_f32_e32 v49, v37, v113
	v_fmac_f32_e32 v48, v102, v100
	v_fmac_f32_e32 v49, v36, v112
	v_fmac_f32_e32 v48, v103, v101
	v_fmac_f32_e32 v49, v114, v38
	v_sub_f32_e32 v41, v41, v48
	v_sub_f32_e32 v42, v102, v42
	v_fmac_f32_e32 v49, v115, v39
	v_sub_f32_e32 v42, v42, v49
	v_mul_f32_e32 v49, v121, v41
	v_fmac_f32_e32 v49, v120, v40
	v_fmac_f32_e32 v49, v102, v122
	v_fmac_f32_e32 v49, v103, v123
	v_sub_f32_e32 v42, v42, v49
	v_mul_f32_e32 v49, v37, v125
	v_fmac_f32_e32 v49, v36, v124
	v_fmac_f32_e32 v49, v126, v38
	v_sub_f32_e32 v43, v103, v43
	v_fmac_f32_e32 v49, v127, v39
	v_sub_f32_e32 v43, v43, v49
	v_mul_f32_e32 v49, v129, v41
	v_fmac_f32_e32 v49, v128, v40
	s_waitcnt lgkmcnt(2)
	v_mul_f32_e32 v48, v41, v213
	v_fmac_f32_e32 v49, v130, v42
	v_fmac_f32_e32 v48, v40, v212
	v_fmac_f32_e32 v49, v103, v131
	v_fmac_f32_e32 v48, v42, v214
	v_sub_f32_e32 v43, v43, v49
	v_fmac_f32_e32 v48, v43, v215
	v_sub_f32_e32 v3, v3, v48
	v_mul_f32_e32 v48, v37, v151
	v_fmac_f32_e32 v48, v36, v150
	v_fmac_f32_e32 v48, v152, v38
	v_sub_f32_e32 v44, v104, v44
	v_fmac_f32_e32 v48, v153, v39
	v_sub_f32_e32 v44, v44, v48
	v_mul_f32_e32 v48, v155, v41
	v_fmac_f32_e32 v48, v154, v40
	v_fmac_f32_e32 v48, v156, v42
	v_fmac_f32_e32 v48, v157, v43
	v_sub_f32_e32 v44, v44, v48
	v_mul_f32_e32 v48, v37, v159
	v_fmac_f32_e32 v48, v36, v158
	v_fmac_f32_e32 v48, v38, v160
	v_sub_f32_e32 v45, v105, v45
	v_fmac_f32_e32 v48, v161, v39
	v_sub_f32_e32 v45, v45, v48
	v_mul_f32_e32 v48, v163, v41
	v_fmac_f32_e32 v48, v162, v40
	v_mul_f32_e32 v49, v37, v171
	v_fmac_f32_e32 v48, v164, v42
	v_fmac_f32_e32 v49, v36, v170
	v_fmac_f32_e32 v48, v165, v43
	v_fmac_f32_e32 v49, v38, v172
	v_sub_f32_e32 v45, v45, v48
	v_mul_f32_e32 v48, v166, v44
	v_sub_f32_e32 v46, v96, v46
	v_fmac_f32_e32 v49, v39, v173
	v_fmac_f32_e32 v48, v105, v167
	v_sub_f32_e32 v46, v46, v49
	v_mul_f32_e32 v49, v175, v41
	v_fmac_f32_e32 v48, v96, v168
	v_fmac_f32_e32 v49, v174, v40
	v_fmac_f32_e32 v48, v97, v169
	v_fmac_f32_e32 v49, v176, v42
	v_sub_f32_e32 v45, v45, v48
	v_fmac_f32_e32 v49, v177, v43
	v_sub_f32_e32 v46, v46, v49
	v_mul_f32_e32 v49, v179, v45
	v_fmac_f32_e32 v49, v178, v44
	v_fmac_f32_e32 v49, v96, v180
	v_fmac_f32_e32 v49, v97, v181
	v_sub_f32_e32 v46, v46, v49
	v_mul_f32_e32 v49, v37, v183
	v_fmac_f32_e32 v49, v36, v182
	v_fmac_f32_e32 v49, v38, v184
	v_sub_f32_e32 v47, v97, v47
	v_fmac_f32_e32 v49, v39, v185
	v_sub_f32_e32 v47, v47, v49
	v_mul_f32_e32 v49, v187, v41
	v_fmac_f32_e32 v49, v40, v186
	v_fmac_f32_e32 v49, v188, v42
	v_fmac_f32_e32 v49, v189, v43
	v_sub_f32_e32 v47, v47, v49
	v_mul_f32_e32 v49, v191, v45
	v_fmac_f32_e32 v49, v190, v44
	s_waitcnt lgkmcnt(1)
	v_mul_f32_e32 v48, v217, v45
	v_fmac_f32_e32 v49, v192, v46
	v_fmac_f32_e32 v48, v216, v44
	v_fmac_f32_e32 v49, v97, v193
	v_fmac_f32_e32 v48, v218, v46
	v_sub_f32_e32 v47, v47, v49
	v_fmac_f32_e32 v48, v219, v47
	v_sub_f32_e32 v3, v3, v48
	v_mul_f32_e32 v48, v37, v195
	v_fmac_f32_e32 v48, v36, v194
	v_fmac_f32_e32 v48, v38, v196
	v_sub_f32_e32 v0, v94, v0
	v_fmac_f32_e32 v48, v39, v197
	v_sub_f32_e32 v0, v0, v48
	v_mul_f32_e32 v48, v199, v41
	v_fmac_f32_e32 v48, v40, v198
	v_fmac_f32_e32 v48, v200, v42
	v_fmac_f32_e32 v48, v201, v43
	v_sub_f32_e32 v0, v0, v48
	v_mul_f32_e32 v48, v203, v45
	v_fmac_f32_e32 v48, v202, v44
	v_fmac_f32_e32 v48, v204, v46
	v_fmac_f32_e32 v48, v205, v47
	v_sub_f32_e32 v0, v0, v48
	v_mul_f32_e32 v48, v37, v247
	v_fmac_f32_e32 v48, v36, v246
	v_mul_f32_e32 v33, v41, v33
	v_fmac_f32_e32 v48, v38, v248
	v_fmac_f32_e32 v33, v40, v32
	v_mul_f32_e32 v29, v29, v45
	v_sub_f32_e32 v1, v95, v1
	v_fmac_f32_e32 v48, v39, v249
	v_fmac_f32_e32 v33, v34, v42
	v_fmac_f32_e32 v29, v28, v44
	v_mul_f32_e32 v24, v24, v0
	v_sub_f32_e32 v1, v1, v48
	v_fmac_f32_e32 v33, v35, v43
	v_fmac_f32_e32 v29, v30, v46
	v_fmac_f32_e32 v24, v95, v25
	v_sub_f32_e32 v1, v1, v33
	v_fmac_f32_e32 v29, v31, v47
	v_fmac_f32_e32 v24, v92, v26
	v_sub_f32_e32 v1, v1, v29
	v_fmac_f32_e32 v24, v93, v27
	v_sub_f32_e32 v1, v1, v24
	s_waitcnt lgkmcnt(0)
	v_mul_f32_e32 v5, v5, v1
	v_fmac_f32_e32 v5, v4, v0
	v_mul_f32_e32 v4, v37, v21
	v_fmac_f32_e32 v4, v36, v20
	v_fmac_f32_e32 v4, v38, v22
	v_sub_f32_e32 v2, v92, v2
	v_fmac_f32_e32 v4, v39, v23
	v_sub_f32_e32 v2, v2, v4
	v_mul_f32_e32 v4, v41, v17
	v_fmac_f32_e32 v4, v40, v16
	v_fmac_f32_e32 v4, v42, v18
	v_fmac_f32_e32 v4, v19, v43
	v_sub_f32_e32 v2, v2, v4
	v_mul_f32_e32 v4, v13, v45
	v_fmac_f32_e32 v4, v12, v44
	v_fmac_f32_e32 v4, v14, v46
	v_fmac_f32_e32 v4, v15, v47
	v_sub_f32_e32 v2, v2, v4
	v_mul_f32_e32 v4, v9, v1
	v_fmac_f32_e32 v4, v8, v0
	v_fmac_f32_e32 v4, v92, v10
	v_cvt_pk_bf16_f32 v8, v1, s0
	v_cvt_pk_bf16_f32 v9, v0, s0
	v_mov_b32_e32 v0, 0x22000000
	v_mov_b32_e32 v1, 0x1e000000
	v_fmac_f32_e32 v4, v93, v11
	v_cndmask_b32_e32 v116, v0, v1, vcc
	v_sub_f32_e32 v2, v2, v4
	v_lshl_add_u64 v[0:1], s[92:93], 0, v[116:117]
	v_fmac_f32_e32 v5, v6, v2
	v_lshl_add_u64 v[0:1], v[0:1], 0, s[0:1]
	v_lshlrev_b32_e32 v116, 1, v90
	v_fmac_f32_e32 v5, v93, v7
	v_lshl_add_u64 v[0:1], v[0:1], 0, v[116:117]
	v_sub_f32_e32 v3, v3, v5
	v_cvt_pk_bf16_f32 v7, v2, s0
	v_add_co_u32_e32 v2, vcc, s67, v0
	v_cvt_pk_bf16_f32 v6, v3, s0
	s_nop 0
	v_addc_co_u32_e32 v3, vcc, 0, v1, vcc
	v_add_co_u32_e32 v4, vcc, s62, v0
	v_addc_co_u32_e32 v5, vcc, 0, v1, vcc
	v_add_co_u32_e32 v0, vcc, s63, v0
	v_cvt_pk_bf16_f32 v21, v36, s0
	s_nop 0
	v_addc_co_u32_e32 v1, vcc, 0, v1, vcc
	v_cvt_pk_bf16_f32 v10, v47, s0
	v_cvt_pk_bf16_f32 v11, v46, s0
	v_cvt_pk_bf16_f32 v12, v45, s0
	v_cvt_pk_bf16_f32 v13, v44, s0
	v_cvt_pk_bf16_f32 v14, v43, s0
	v_cvt_pk_bf16_f32 v15, v42, s0
	v_cvt_pk_bf16_f32 v16, v41, s0
	v_cvt_pk_bf16_f32 v17, v40, s0
	v_cvt_pk_bf16_f32 v18, v39, s0
	v_cvt_pk_bf16_f32 v19, v38, s0
	v_cvt_pk_bf16_f32 v20, v37, s0
	s_barrier
	v_and_b32_e32 v2, 63, v208
	v_lshrrev_b32_e32 v3, 6, v208
	v_lshlrev_b32_e32 v3, 13, v3
	v_lshl_add_u32 v4, v2, 1, v3
	ds_write_b16 v4, v63
	ds_write_b16 v4, v65 offset:128
	ds_write_b16 v4, v67 offset:256
	ds_write_b16 v4, v91 offset:384
	ds_write_b16 v4, v149 offset:512
	ds_write_b16 v4, v74 offset:640
	ds_write_b16 v4, v78 offset:768
	ds_write_b16 v4, v80 offset:896
	ds_write_b16 v4, v133 offset:1024
	ds_write_b16 v4, v134 offset:1152
	ds_write_b16 v4, v136 offset:1280
	ds_write_b16 v4, v137 offset:1408
	ds_write_b16 v4, v142 offset:1536
	ds_write_b16 v4, v143 offset:1664
	ds_write_b16 v4, v144 offset:1792
	ds_write_b16 v4, v145 offset:1920
	ds_write_b16 v4, v82 offset:2048
	ds_write_b16 v4, v84 offset:2176
	ds_write_b16 v4, v118 offset:2304
	ds_write_b16 v4, v132 offset:2432
	ds_write_b16 v4, v138 offset:2560
	ds_write_b16 v4, v139 offset:2688
	ds_write_b16 v4, v140 offset:2816
	ds_write_b16 v4, v141 offset:2944
	ds_write_b16 v4, v60 offset:3072
	ds_write_b16 v4, v61 offset:3200
	ds_write_b16 v4, v72 offset:3328
	ds_write_b16 v4, v73 offset:3456
	ds_write_b16 v4, v75 offset:3584
	ds_write_b16 v4, v76 offset:3712
	ds_write_b16 v4, v77 offset:3840
	ds_write_b16 v4, v79 offset:3968
	ds_write_b16 v4, v81 offset:4096
	ds_write_b16 v4, v83 offset:4224
	ds_write_b16 v4, v85 offset:4352
	ds_write_b16 v4, v119 offset:4480
	ds_write_b16 v4, v135 offset:4608
	ds_write_b16 v4, v146 offset:4736
	ds_write_b16 v4, v147 offset:4864
	ds_write_b16 v4, v64 offset:4992
	ds_write_b16 v4, v148 offset:5120
	ds_write_b16 v4, v206 offset:5248
	ds_write_b16 v4, v207 offset:5376
	ds_write_b16 v4, v209 offset:5504
	ds_write_b16 v4, v220 offset:5632
	ds_write_b16 v4, v66 offset:5760
	ds_write_b16 v4, v221 offset:5888
	ds_write_b16 v4, v222 offset:6016
	ds_write_b16 v4, v21 offset:6144
	ds_write_b16 v4, v20 offset:6272
	ds_write_b16 v4, v19 offset:6400
	ds_write_b16 v4, v18 offset:6528
	ds_write_b16 v4, v17 offset:6656
	ds_write_b16 v4, v16 offset:6784
	ds_write_b16 v4, v15 offset:6912
	ds_write_b16 v4, v14 offset:7040
	ds_write_b16 v4, v13 offset:7168
	ds_write_b16 v4, v12 offset:7296
	ds_write_b16 v4, v11 offset:7424
	ds_write_b16 v4, v10 offset:7552
	ds_write_b16 v4, v9 offset:7680
	ds_write_b16 v4, v8 offset:7808
	ds_write_b16 v4, v7 offset:7936
	ds_write_b16 v4, v6 offset:8064
	v_lshrrev_b32_e32 v5, 3, v2
	v_and_b32_e32 v4, 7, v2
	v_lshlrev_b32_e32 v4, 4, v4
	v_lshl_add_u32 v3, v5, 7, v3
	v_add_u32_e32 v3, v3, v4
	v_lshlrev_b32_e32 v2, 1, v2
	v_lshl_add_u32 v5, v5, 8, v4
	v_sub_u32_e32 v5, v5, v2
	v_add_u32_e32 v5, 0xffffd000, v5
	v_ashrrev_i32_e32 v4, 31, v5
	v_add_co_u32_e32 v0, vcc, v0, v5
	s_nop 1
	v_addc_co_u32_e32 v1, vcc, v1, v4, vcc
	s_waitcnt lgkmcnt(0)
	ds_read_b128 v[8:11], v3
	ds_read_b128 v[12:15], v3 offset:1024
	ds_read_b128 v[16:19], v3 offset:2048
	ds_read_b128 v[64:67], v3 offset:3072
	ds_read_b128 v[72:75], v3 offset:4096
	ds_read_b128 v[76:79], v3 offset:5120
	ds_read_b128 v[80:83], v3 offset:6144
	ds_read_b128 v[132:135], v3 offset:7168
	s_waitcnt lgkmcnt(0)
	global_store_dwordx4 v[0:1], v[8:11], off
	global_store_dwordx4 v[0:1], v[12:15], off offset:2048
	v_add_co_u32_e32 v0, vcc, 0x1000, v0
	s_nop 1
	v_addc_co_u32_e32 v1, vcc, 0, v1, vcc
	global_store_dwordx4 v[0:1], v[16:19], off
	global_store_dwordx4 v[0:1], v[64:67], off offset:2048
	v_add_co_u32_e32 v0, vcc, 0x1000, v0
	s_nop 1
	v_addc_co_u32_e32 v1, vcc, 0, v1, vcc
	global_store_dwordx4 v[0:1], v[72:75], off
	global_store_dwordx4 v[0:1], v[76:79], off offset:2048
	v_add_co_u32_e32 v0, vcc, 0x1000, v0
	s_nop 1
	v_addc_co_u32_e32 v1, vcc, 0, v1, vcc
	global_store_dwordx4 v[0:1], v[80:83], off
	global_store_dwordx4 v[0:1], v[132:135], off offset:2048
	s_cbranch_scc1 .LBB0_294

.LBB0_302:
	s_mov_b32 s27, s96
.Lsc_item:
	s_cmp_lt_u32 s27, 256
	s_cbranch_scc0 .LBB0_308
	v_and_b32_e32 v251, 63, v208
	v_lshrrev_b32_e32 v252, 6, v208
	v_and_b32_e32 v253, 15, v251
	v_lshrrev_b32_e32 v251, 4, v251
	v_lshl_add_u32 v250, v252, 4, v253
	v_lshlrev_b32_e32 v209, 4, v251
	v_mul_u32_u24_e32 v247, 272, v253
	v_add_u32_e32 v209, v209, v247
	v_lshlrev_b32_e32 v210, 1, v250
	v_mul_u32_u24_e32 v247, 576, v251
	v_add_u32_e32 v210, v210, v247
	v_add_u32_e32 v210, 4352, v210
	v_lshlrev_b32_e32 v211, 4, v251
	v_mul_u32_u24_e32 v247, 144, v253
	v_add_u32_e32 v211, v211, v247
	v_add_u32_e32 v211, 4352, v211
	v_lshl_add_u32 v212, v252, 5, v253
	v_lshlrev_b32_e32 v212, 1, v212
	v_mul_u32_u24_e32 v247, 1088, v251
	v_add_u32_e32 v212, v212, v247
	v_lshlrev_b32_e32 v213, 4, v251
	v_lshl_add_u32 v213, v250, 8, v213
	v_lshlrev_b32_e32 v214, 4, v251
	v_lshl_add_u32 v214, v250, 7, v214
	v_lshl_add_u32 v215, v252, 5, v253
	v_lshlrev_b32_e32 v215, 7, v215
	v_lshl_add_u32 v215, v251, 4, v215
	v_lshlrev_b32_e32 v248, 3, v251
	v_lshl_add_u32 v248, v250, 8, v248
	v_lshlrev_b32_e32 v249, 3, v251
	v_lshl_add_u32 v249, v250, 11, v249
	s_and_b32 s0, s27, 7
	s_lshr_b32 s23, s27, 5
	s_lshl_b32 s23, s23, 3
	s_add_i32 s0, s0, s23
	s_lshr_b32 s23, s27, 3
	s_and_b32 s23, s23, 3
	s_lshl_b32 s23, s23, 6
	s_lshl_b32 s24, s0, 20
	s_add_u32 s8, s92, s24
	s_addc_u32 s9, s93, 0
	s_add_u32 s10, s8, 0x26000000
	s_addc_u32 s11, s9, 0
	s_add_u32 s12, s8, 0x2a000000
	s_addc_u32 s13, s9, 0
	s_add_u32 s16, s8, 0x1e000000
	s_addc_u32 s17, s9, 0
	s_add_u32 s16, s16, s23
	s_addc_u32 s17, s17, 0
	s_add_u32 s8, s8, 0x22000000
	s_addc_u32 s9, s9, 0
	s_lshl_b32 s24, s0, 19
	s_add_u32 s14, s92, s24
	s_addc_u32 s15, s93, 0
	s_add_u32 s14, s14, 0x2e000000
	s_addc_u32 s15, s15, 0
	s_lshl_b32 s24, s0, 8
	s_add_u32 s18, s92, s24
	s_addc_u32 s19, s93, 0
	s_add_u32 s18, s18, 0x36f00000
	s_addc_u32 s19, s19, 0
	s_lshr_b32 s24, s0, 2
	s_lshl_b32 s24, s24, 23
	s_and_b32 s25, s0, 3
	s_lshl_b32 s25, s25, 8
	s_add_i32 s24, s24, s25
	s_add_i32 s24, s24, s23
	s_add_i32 s24, s24, 1024
	s_add_u32 s20, s92, s24
	s_addc_u32 s21, s93, 0
	v_mov_b32_e32 v250, 0
	v_mov_b32_e32 v240, 0
	v_mov_b32_e32 v241, 0
	v_mov_b32_e32 v242, 0
	v_mov_b32_e32 v243, 0
	v_lshlrev_b32_e32 v251, 4, v208
	ds_write_b128 v251, v[240:243] offset:0
	ds_write_b128 v251, v[240:243] offset:4096
	ds_write_b128 v251, v[240:243] offset:8192
	ds_write_b128 v251, v[240:243] offset:12288
	v_mov_b32_e32 v192, 0
	v_mov_b32_e32 v193, 0
	v_mov_b32_e32 v194, 0
	v_mov_b32_e32 v195, 0
	v_mov_b32_e32 v196, 0
	v_mov_b32_e32 v197, 0
	v_mov_b32_e32 v198, 0
	v_mov_b32_e32 v199, 0
	v_mov_b32_e32 v200, 0
	v_mov_b32_e32 v201, 0
	v_mov_b32_e32 v202, 0
	v_mov_b32_e32 v203, 0
	v_mov_b32_e32 v204, 0
	v_mov_b32_e32 v205, 0
	v_mov_b32_e32 v206, 0
	v_mov_b32_e32 v207, 0
	s_mov_b32 s22, 0
	global_load_dwordx4 v[0:3], v213, s[8:9] offset:0
	global_load_dwordx4 v[4:7], v213, s[8:9] offset:64
	global_load_dwordx4 v[8:11], v213, s[8:9] offset:128
	global_load_dwordx4 v[12:15], v213, s[8:9] offset:192
	global_load_dwordx4 v[16:19], v213, s[10:11] offset:0
	global_load_dwordx4 v[20:23], v213, s[10:11] offset:64
	global_load_dwordx4 v[24:27], v213, s[10:11] offset:128
	global_load_dwordx4 v[28:31], v213, s[10:11] offset:192
	global_load_dwordx4 v[32:35], v214, s[14:15] offset:0
	global_load_dwordx4 v[36:39], v214, s[14:15] offset:64
	global_load_dwordx4 v[40:43], v215, s[12:13] offset:0
	global_load_dwordx4 v[44:47], v215, s[12:13] offset:64
	global_load_dwordx4 v[48:51], v215, s[12:13] offset:2048
	global_load_dwordx4 v[52:55], v215, s[12:13] offset:2112
	global_load_dwordx2 v[56:57], v248, s[16:17] offset:0
	global_load_dwordx2 v[58:59], v248, s[16:17] offset:32
	global_load_dword v62, v250, s[18:19]
	s_cmp_lt_u32 s22, 63
	s_cselect_b32 s0, 0x4000, 0
	s_cselect_b32 s23, 0x2000, 0
	s_cselect_b32 s24, 4, 0
	s_add_u32 s8, s8, s0
	s_addc_u32 s9, s9, 0
	s_add_u32 s10, s10, s0
	s_addc_u32 s11, s11, 0
	s_add_u32 s12, s12, s0
	s_addc_u32 s13, s13, 0
	s_add_u32 s16, s16, s0
	s_addc_u32 s17, s17, 0
	s_add_u32 s14, s14, s23
	s_addc_u32 s15, s15, 0
	s_add_u32 s18, s18, s24
	s_addc_u32 s19, s19, 0
	s_add_i32 s22, s22, 1
	global_load_dwordx4 v[64:67], v213, s[8:9] offset:0
	global_load_dwordx4 v[68:71], v213, s[8:9] offset:64
	global_load_dwordx4 v[72:75], v213, s[8:9] offset:128
	global_load_dwordx4 v[76:79], v213, s[8:9] offset:192
	global_load_dwordx4 v[80:83], v213, s[10:11] offset:0
	global_load_dwordx4 v[84:87], v213, s[10:11] offset:64
	global_load_dwordx4 v[88:91], v213, s[10:11] offset:128
	global_load_dwordx4 v[92:95], v213, s[10:11] offset:192
	global_load_dwordx4 v[96:99], v214, s[14:15] offset:0
	global_load_dwordx4 v[100:103], v214, s[14:15] offset:64
	global_load_dwordx4 v[104:107], v215, s[12:13] offset:0
	global_load_dwordx4 v[108:111], v215, s[12:13] offset:64
	global_load_dwordx4 v[112:115], v215, s[12:13] offset:2048
	global_load_dwordx4 v[116:119], v215, s[12:13] offset:2112
	global_load_dwordx2 v[120:121], v248, s[16:17] offset:0
	global_load_dwordx2 v[122:123], v248, s[16:17] offset:32
	global_load_dword v126, v250, s[18:19]
	s_cmp_lt_u32 s22, 63
	s_cselect_b32 s0, 0x4000, 0
	s_cselect_b32 s23, 0x2000, 0
	s_cselect_b32 s24, 4, 0
	s_add_u32 s8, s8, s0
	s_addc_u32 s9, s9, 0
	s_add_u32 s10, s10, s0
	s_addc_u32 s11, s11, 0
	s_add_u32 s12, s12, s0
	s_addc_u32 s13, s13, 0
	s_add_u32 s16, s16, s0
	s_addc_u32 s17, s17, 0
	s_add_u32 s14, s14, s23
	s_addc_u32 s15, s15, 0
	s_add_u32 s18, s18, s24
	s_addc_u32 s19, s19, 0
	s_add_i32 s22, s22, 1
	s_mov_b32 s26, 0
	s_waitcnt lgkmcnt(0)
	s_barrier
.Lsc_loop:
	global_load_dwordx4 v[128:131], v213, s[8:9] offset:0
	global_load_dwordx4 v[132:135], v213, s[8:9] offset:64
	global_load_dwordx4 v[136:139], v213, s[8:9] offset:128
	global_load_dwordx4 v[140:143], v213, s[8:9] offset:192
	global_load_dwordx4 v[144:147], v213, s[10:11] offset:0
	global_load_dwordx4 v[148:151], v213, s[10:11] offset:64
	global_load_dwordx4 v[152:155], v213, s[10:11] offset:128
	global_load_dwordx4 v[156:159], v213, s[10:11] offset:192
	global_load_dwordx4 v[160:163], v214, s[14:15] offset:0
	global_load_dwordx4 v[164:167], v214, s[14:15] offset:64
	global_load_dwordx4 v[168:171], v215, s[12:13] offset:0
	global_load_dwordx4 v[172:175], v215, s[12:13] offset:64
	global_load_dwordx4 v[176:179], v215, s[12:13] offset:2048
	global_load_dwordx4 v[180:183], v215, s[12:13] offset:2112
	global_load_dwordx2 v[184:185], v248, s[16:17] offset:0
	global_load_dwordx2 v[186:187], v248, s[16:17] offset:32
	global_load_dword v190, v250, s[18:19]
	s_cmp_lt_u32 s22, 63
	s_cselect_b32 s0, 0x4000, 0
	s_cselect_b32 s23, 0x2000, 0
	s_cselect_b32 s24, 4, 0
	s_add_u32 s8, s8, s0
	s_addc_u32 s9, s9, 0
	s_add_u32 s10, s10, s0
	s_addc_u32 s11, s11, 0
	s_add_u32 s12, s12, s0
	s_addc_u32 s13, s13, 0
	s_add_u32 s16, s16, s0
	s_addc_u32 s17, s17, 0
	s_add_u32 s14, s14, s23
	s_addc_u32 s15, s15, 0
	s_add_u32 s18, s18, s24
	s_addc_u32 s19, s19, 0
	s_add_i32 s22, s22, 1
	s_waitcnt vmcnt(34)
	ds_read_b128 v[216:219], v209 offset:0
	ds_read_b128 v[220:223], v209 offset:64
	ds_read_b128 v[224:227], v209 offset:128
	ds_read_b128 v[228:231], v209 offset:192
	s_waitcnt lgkmcnt(0)
	v_mfma_f32_16x16x32_bf16 v[232:235], v[216:219], v[0:3], 0
	v_mfma_f32_16x16x32_bf16 v[236:239], v[216:219], v[16:19], 0
	v_mfma_f32_16x16x32_bf16 v[232:235], v[220:223], v[4:7], v[232:235]
	v_mfma_f32_16x16x32_bf16 v[236:239], v[220:223], v[20:23], v[236:239]
	v_mfma_f32_16x16x32_bf16 v[232:235], v[224:227], v[8:11], v[232:235]
	v_mfma_f32_16x16x32_bf16 v[236:239], v[224:227], v[24:27], v[236:239]
	v_mfma_f32_16x16x32_bf16 v[232:235], v[228:231], v[12:15], v[232:235]
	v_mfma_f32_16x16x32_bf16 v[236:239], v[228:231], v[28:31], v[236:239]
	s_nop 7
	s_nop 1
	v_lshlrev_b32_e32 v244, 16, v56
	v_and_b32_e32 v245, 0xffff0000, v56
	v_lshlrev_b32_e32 v246, 16, v57
	v_and_b32_e32 v247, 0xffff0000, v57
	v_sub_f32_e32 v244, v244, v232
	v_sub_f32_e32 v245, v245, v233
	v_sub_f32_e32 v246, v246, v234
	v_sub_f32_e32 v247, v247, v235
	v_cvt_pk_bf16_f32 v244, v244, v245
	v_cvt_pk_bf16_f32 v246, v246, v247
	ds_write_b16 v210, v244 offset:0
	ds_write_b16_d16_hi v210, v244 offset:144
	ds_write_b16 v210, v246 offset:288
	ds_write_b16_d16_hi v210, v246 offset:432
	ds_read_b128 v[216:219], v209 offset:6656
	ds_read_b128 v[220:223], v209 offset:6720
	ds_read_b128 v[224:227], v209 offset:6784
	ds_read_b128 v[228:231], v209 offset:6848
	s_waitcnt lgkmcnt(0)
	v_mfma_f32_16x16x32_bf16 v[232:235], v[216:219], v[0:3], 0
	v_mfma_f32_16x16x32_bf16 v[240:243], v[216:219], v[16:19], 0
	v_mfma_f32_16x16x32_bf16 v[232:235], v[220:223], v[4:7], v[232:235]
	v_mfma_f32_16x16x32_bf16 v[240:243], v[220:223], v[20:23], v[240:243]
	v_mfma_f32_16x16x32_bf16 v[232:235], v[224:227], v[8:11], v[232:235]
	v_mfma_f32_16x16x32_bf16 v[240:243], v[224:227], v[24:27], v[240:243]
	v_mfma_f32_16x16x32_bf16 v[232:235], v[228:231], v[12:15], v[232:235]
	v_mfma_f32_16x16x32_bf16 v[240:243], v[228:231], v[28:31], v[240:243]
	s_nop 7
	s_nop 1
	v_lshlrev_b32_e32 v244, 16, v58
	v_and_b32_e32 v245, 0xffff0000, v58
	v_lshlrev_b32_e32 v246, 16, v59
	v_and_b32_e32 v247, 0xffff0000, v59
	v_sub_f32_e32 v244, v244, v232
	v_sub_f32_e32 v245, v245, v233
	v_sub_f32_e32 v246, v246, v234
	v_sub_f32_e32 v247, v247, v235
	v_cvt_pk_bf16_f32 v244, v244, v245
	v_cvt_pk_bf16_f32 v246, v246, v247
	ds_write_b16 v210, v244 offset:6656
	ds_write_b16_d16_hi v210, v244 offset:6800
	ds_write_b16 v210, v246 offset:6944
	ds_write_b16_d16_hi v210, v246 offset:7088
	s_waitcnt lgkmcnt(0)
	s_barrier
	ds_read_b128 v[216:219], v211 offset:0
	ds_read_b128 v[220:223], v211 offset:64
	v_mul_f32_e32 v192, v62, v192
	v_mul_f32_e32 v193, v62, v193
	v_mul_f32_e32 v194, v62, v194
	v_mul_f32_e32 v195, v62, v195
	v_mul_f32_e32 v196, v62, v196
	v_mul_f32_e32 v197, v62, v197
	v_mul_f32_e32 v198, v62, v198
	v_mul_f32_e32 v199, v62, v199
	s_waitcnt lgkmcnt(0)
	v_mfma_f32_16x16x32_bf16 v[236:239], v[216:219], v[32:35], v[236:239]
	v_mfma_f32_16x16x32_bf16 v[192:195], v[216:219], v[40:43], v[192:195]
	v_mfma_f32_16x16x32_bf16 v[196:199], v[216:219], v[48:51], v[196:199]
	v_mfma_f32_16x16x32_bf16 v[236:239], v[220:223], v[36:39], v[236:239]
	v_mfma_f32_16x16x32_bf16 v[192:195], v[220:223], v[44:47], v[192:195]
	v_mfma_f32_16x16x32_bf16 v[196:199], v[220:223], v[52:55], v[196:199]
	s_nop 7
	s_nop 1
	v_cvt_pk_bf16_f32 v244, v236, v237
	v_cvt_pk_bf16_f32 v245, v238, v239
	global_store_dwordx2 v249, v[244:245], s[20:21] offset:0
	v_cvt_pk_bf16_f32 v246, v192, v193
	v_cvt_pk_bf16_f32 v247, v194, v195
	ds_write_b16 v212, v246 offset:0
	ds_write_b16_d16_hi v212, v246 offset:272
	ds_write_b16 v212, v247 offset:544
	ds_write_b16_d16_hi v212, v247 offset:816
	v_cvt_pk_bf16_f32 v246, v196, v197
	v_cvt_pk_bf16_f32 v247, v198, v199
	ds_write_b16 v212, v246 offset:32
	ds_write_b16_d16_hi v212, v246 offset:304
	ds_write_b16 v212, v247 offset:576
	ds_write_b16_d16_hi v212, v247 offset:848
	ds_read_b128 v[216:219], v211 offset:6656
	ds_read_b128 v[220:223], v211 offset:6720
	v_mul_f32_e32 v200, v62, v200
	v_mul_f32_e32 v201, v62, v201
	v_mul_f32_e32 v202, v62, v202
	v_mul_f32_e32 v203, v62, v203
	v_mul_f32_e32 v204, v62, v204
	v_mul_f32_e32 v205, v62, v205
	v_mul_f32_e32 v206, v62, v206
	v_mul_f32_e32 v207, v62, v207
	s_waitcnt lgkmcnt(0)
	v_mfma_f32_16x16x32_bf16 v[240:243], v[216:219], v[32:35], v[240:243]
	v_mfma_f32_16x16x32_bf16 v[200:203], v[216:219], v[40:43], v[200:203]
	v_mfma_f32_16x16x32_bf16 v[204:207], v[216:219], v[48:51], v[204:207]
	v_mfma_f32_16x16x32_bf16 v[240:243], v[220:223], v[36:39], v[240:243]
	v_mfma_f32_16x16x32_bf16 v[200:203], v[220:223], v[44:47], v[200:203]
	v_mfma_f32_16x16x32_bf16 v[204:207], v[220:223], v[52:55], v[204:207]
	s_nop 7
	s_nop 1
	v_cvt_pk_bf16_f32 v244, v240, v241
	v_cvt_pk_bf16_f32 v245, v242, v243
	global_store_dwordx2 v249, v[244:245], s[20:21] offset:32
	v_cvt_pk_bf16_f32 v246, v200, v201
	v_cvt_pk_bf16_f32 v247, v202, v203
	ds_write_b16 v212, v246 offset:6656
	ds_write_b16_d16_hi v212, v246 offset:6928
	ds_write_b16 v212, v247 offset:7200
	ds_write_b16_d16_hi v212, v247 offset:7472
	v_cvt_pk_bf16_f32 v246, v204, v205
	v_cvt_pk_bf16_f32 v247, v206, v207
	ds_write_b16 v212, v246 offset:6688
	ds_write_b16_d16_hi v212, v246 offset:6960
	ds_write_b16 v212, v247 offset:7232
	ds_write_b16_d16_hi v212, v247 offset:7504
	s_add_u32 s20, s20, 0x20000
	s_addc_u32 s21, s21, 0
	s_add_i32 s26, s26, 1
	s_waitcnt lgkmcnt(0)
	s_barrier
	global_load_dwordx4 v[0:3], v213, s[8:9] offset:0
	global_load_dwordx4 v[4:7], v213, s[8:9] offset:64
	global_load_dwordx4 v[8:11], v213, s[8:9] offset:128
	global_load_dwordx4 v[12:15], v213, s[8:9] offset:192
	global_load_dwordx4 v[16:19], v213, s[10:11] offset:0
	global_load_dwordx4 v[20:23], v213, s[10:11] offset:64
	global_load_dwordx4 v[24:27], v213, s[10:11] offset:128
	global_load_dwordx4 v[28:31], v213, s[10:11] offset:192
	global_load_dwordx4 v[32:35], v214, s[14:15] offset:0
	global_load_dwordx4 v[36:39], v214, s[14:15] offset:64
	global_load_dwordx4 v[40:43], v215, s[12:13] offset:0
	global_load_dwordx4 v[44:47], v215, s[12:13] offset:64
	global_load_dwordx4 v[48:51], v215, s[12:13] offset:2048
	global_load_dwordx4 v[52:55], v215, s[12:13] offset:2112
	global_load_dwordx2 v[56:57], v248, s[16:17] offset:0
	global_load_dwordx2 v[58:59], v248, s[16:17] offset:32
	global_load_dword v62, v250, s[18:19]
	s_cmp_lt_u32 s22, 63
	s_cselect_b32 s0, 0x4000, 0
	s_cselect_b32 s23, 0x2000, 0
	s_cselect_b32 s24, 4, 0
	s_add_u32 s8, s8, s0
	s_addc_u32 s9, s9, 0
	s_add_u32 s10, s10, s0
	s_addc_u32 s11, s11, 0
	s_add_u32 s12, s12, s0
	s_addc_u32 s13, s13, 0
	s_add_u32 s16, s16, s0
	s_addc_u32 s17, s17, 0
	s_add_u32 s14, s14, s23
	s_addc_u32 s15, s15, 0
	s_add_u32 s18, s18, s24
	s_addc_u32 s19, s19, 0
	s_add_i32 s22, s22, 1
	s_waitcnt vmcnt(34)
	ds_read_b128 v[216:219], v209 offset:0
	ds_read_b128 v[220:223], v209 offset:64
	ds_read_b128 v[224:227], v209 offset:128
	ds_read_b128 v[228:231], v209 offset:192
	s_waitcnt lgkmcnt(0)
	v_mfma_f32_16x16x32_bf16 v[232:235], v[216:219], v[64:67], 0
	v_mfma_f32_16x16x32_bf16 v[236:239], v[216:219], v[80:83], 0
	v_mfma_f32_16x16x32_bf16 v[232:235], v[220:223], v[68:71], v[232:235]
	v_mfma_f32_16x16x32_bf16 v[236:239], v[220:223], v[84:87], v[236:239]
	v_mfma_f32_16x16x32_bf16 v[232:235], v[224:227], v[72:75], v[232:235]
	v_mfma_f32_16x16x32_bf16 v[236:239], v[224:227], v[88:91], v[236:239]
	v_mfma_f32_16x16x32_bf16 v[232:235], v[228:231], v[76:79], v[232:235]
	v_mfma_f32_16x16x32_bf16 v[236:239], v[228:231], v[92:95], v[236:239]
	s_nop 7
	s_nop 1
	v_lshlrev_b32_e32 v244, 16, v120
	v_and_b32_e32 v245, 0xffff0000, v120
	v_lshlrev_b32_e32 v246, 16, v121
	v_and_b32_e32 v247, 0xffff0000, v121
	v_sub_f32_e32 v244, v244, v232
	v_sub_f32_e32 v245, v245, v233
	v_sub_f32_e32 v246, v246, v234
	v_sub_f32_e32 v247, v247, v235
	v_cvt_pk_bf16_f32 v244, v244, v245
	v_cvt_pk_bf16_f32 v246, v246, v247
	ds_write_b16 v210, v244 offset:0
	ds_write_b16_d16_hi v210, v244 offset:144
	ds_write_b16 v210, v246 offset:288
	ds_write_b16_d16_hi v210, v246 offset:432
	ds_read_b128 v[216:219], v209 offset:6656
	ds_read_b128 v[220:223], v209 offset:6720
	ds_read_b128 v[224:227], v209 offset:6784
	ds_read_b128 v[228:231], v209 offset:6848
	s_waitcnt lgkmcnt(0)
	v_mfma_f32_16x16x32_bf16 v[232:235], v[216:219], v[64:67], 0
	v_mfma_f32_16x16x32_bf16 v[240:243], v[216:219], v[80:83], 0
	v_mfma_f32_16x16x32_bf16 v[232:235], v[220:223], v[68:71], v[232:235]
	v_mfma_f32_16x16x32_bf16 v[240:243], v[220:223], v[84:87], v[240:243]
	v_mfma_f32_16x16x32_bf16 v[232:235], v[224:227], v[72:75], v[232:235]
	v_mfma_f32_16x16x32_bf16 v[240:243], v[224:227], v[88:91], v[240:243]
	v_mfma_f32_16x16x32_bf16 v[232:235], v[228:231], v[76:79], v[232:235]
	v_mfma_f32_16x16x32_bf16 v[240:243], v[228:231], v[92:95], v[240:243]
	s_nop 7
	s_nop 1
	v_lshlrev_b32_e32 v244, 16, v122
	v_and_b32_e32 v245, 0xffff0000, v122
	v_lshlrev_b32_e32 v246, 16, v123
	v_and_b32_e32 v247, 0xffff0000, v123
	v_sub_f32_e32 v244, v244, v232
	v_sub_f32_e32 v245, v245, v233
	v_sub_f32_e32 v246, v246, v234
	v_sub_f32_e32 v247, v247, v235
	v_cvt_pk_bf16_f32 v244, v244, v245
	v_cvt_pk_bf16_f32 v246, v246, v247
	ds_write_b16 v210, v244 offset:6656
	ds_write_b16_d16_hi v210, v244 offset:6800
	ds_write_b16 v210, v246 offset:6944
	ds_write_b16_d16_hi v210, v246 offset:7088
	s_waitcnt lgkmcnt(0)
	s_barrier
	ds_read_b128 v[216:219], v211 offset:0
	ds_read_b128 v[220:223], v211 offset:64
	v_mul_f32_e32 v192, v126, v192
	v_mul_f32_e32 v193, v126, v193
	v_mul_f32_e32 v194, v126, v194
	v_mul_f32_e32 v195, v126, v195
	v_mul_f32_e32 v196, v126, v196
	v_mul_f32_e32 v197, v126, v197
	v_mul_f32_e32 v198, v126, v198
	v_mul_f32_e32 v199, v126, v199
	s_waitcnt lgkmcnt(0)
	v_mfma_f32_16x16x32_bf16 v[236:239], v[216:219], v[96:99], v[236:239]
	v_mfma_f32_16x16x32_bf16 v[192:195], v[216:219], v[104:107], v[192:195]
	v_mfma_f32_16x16x32_bf16 v[196:199], v[216:219], v[112:115], v[196:199]
	v_mfma_f32_16x16x32_bf16 v[236:239], v[220:223], v[100:103], v[236:239]
	v_mfma_f32_16x16x32_bf16 v[192:195], v[220:223], v[108:111], v[192:195]
	v_mfma_f32_16x16x32_bf16 v[196:199], v[220:223], v[116:119], v[196:199]
	s_nop 7
	s_nop 1
	v_cvt_pk_bf16_f32 v244, v236, v237
	v_cvt_pk_bf16_f32 v245, v238, v239
	global_store_dwordx2 v249, v[244:245], s[20:21] offset:0
	v_cvt_pk_bf16_f32 v246, v192, v193
	v_cvt_pk_bf16_f32 v247, v194, v195
	ds_write_b16 v212, v246 offset:0
	ds_write_b16_d16_hi v212, v246 offset:272
	ds_write_b16 v212, v247 offset:544
	ds_write_b16_d16_hi v212, v247 offset:816
	v_cvt_pk_bf16_f32 v246, v196, v197
	v_cvt_pk_bf16_f32 v247, v198, v199
	ds_write_b16 v212, v246 offset:32
	ds_write_b16_d16_hi v212, v246 offset:304
	ds_write_b16 v212, v247 offset:576
	ds_write_b16_d16_hi v212, v247 offset:848
	ds_read_b128 v[216:219], v211 offset:6656
	ds_read_b128 v[220:223], v211 offset:6720
	v_mul_f32_e32 v200, v126, v200
	v_mul_f32_e32 v201, v126, v201
	v_mul_f32_e32 v202, v126, v202
	v_mul_f32_e32 v203, v126, v203
	v_mul_f32_e32 v204, v126, v204
	v_mul_f32_e32 v205, v126, v205
	v_mul_f32_e32 v206, v126, v206
	v_mul_f32_e32 v207, v126, v207
	s_waitcnt lgkmcnt(0)
	v_mfma_f32_16x16x32_bf16 v[240:243], v[216:219], v[96:99], v[240:243]
	v_mfma_f32_16x16x32_bf16 v[200:203], v[216:219], v[104:107], v[200:203]
	v_mfma_f32_16x16x32_bf16 v[204:207], v[216:219], v[112:115], v[204:207]
	v_mfma_f32_16x16x32_bf16 v[240:243], v[220:223], v[100:103], v[240:243]
	v_mfma_f32_16x16x32_bf16 v[200:203], v[220:223], v[108:111], v[200:203]
	v_mfma_f32_16x16x32_bf16 v[204:207], v[220:223], v[116:119], v[204:207]
	s_nop 7
	s_nop 1
	v_cvt_pk_bf16_f32 v244, v240, v241
	v_cvt_pk_bf16_f32 v245, v242, v243
	global_store_dwordx2 v249, v[244:245], s[20:21] offset:32
	v_cvt_pk_bf16_f32 v246, v200, v201
	v_cvt_pk_bf16_f32 v247, v202, v203
	ds_write_b16 v212, v246 offset:6656
	ds_write_b16_d16_hi v212, v246 offset:6928
	ds_write_b16 v212, v247 offset:7200
	ds_write_b16_d16_hi v212, v247 offset:7472
	v_cvt_pk_bf16_f32 v246, v204, v205
	v_cvt_pk_bf16_f32 v247, v206, v207
	ds_write_b16 v212, v246 offset:6688
	ds_write_b16_d16_hi v212, v246 offset:6960
	ds_write_b16 v212, v247 offset:7232
	ds_write_b16_d16_hi v212, v247 offset:7504
	s_add_u32 s20, s20, 0x20000
	s_addc_u32 s21, s21, 0
	s_add_i32 s26, s26, 1
	s_waitcnt lgkmcnt(0)
	s_barrier
	global_load_dwordx4 v[64:67], v213, s[8:9] offset:0
	global_load_dwordx4 v[68:71], v213, s[8:9] offset:64
	global_load_dwordx4 v[72:75], v213, s[8:9] offset:128
	global_load_dwordx4 v[76:79], v213, s[8:9] offset:192
	global_load_dwordx4 v[80:83], v213, s[10:11] offset:0
	global_load_dwordx4 v[84:87], v213, s[10:11] offset:64
	global_load_dwordx4 v[88:91], v213, s[10:11] offset:128
	global_load_dwordx4 v[92:95], v213, s[10:11] offset:192
	global_load_dwordx4 v[96:99], v214, s[14:15] offset:0
	global_load_dwordx4 v[100:103], v214, s[14:15] offset:64
	global_load_dwordx4 v[104:107], v215, s[12:13] offset:0
	global_load_dwordx4 v[108:111], v215, s[12:13] offset:64
	global_load_dwordx4 v[112:115], v215, s[12:13] offset:2048
	global_load_dwordx4 v[116:119], v215, s[12:13] offset:2112
	global_load_dwordx2 v[120:121], v248, s[16:17] offset:0
	global_load_dwordx2 v[122:123], v248, s[16:17] offset:32
	global_load_dword v126, v250, s[18:19]
	s_cmp_lt_u32 s22, 63
	s_cselect_b32 s0, 0x4000, 0
	s_cselect_b32 s23, 0x2000, 0
	s_cselect_b32 s24, 4, 0
	s_add_u32 s8, s8, s0
	s_addc_u32 s9, s9, 0
	s_add_u32 s10, s10, s0
	s_addc_u32 s11, s11, 0
	s_add_u32 s12, s12, s0
	s_addc_u32 s13, s13, 0
	s_add_u32 s16, s16, s0
	s_addc_u32 s17, s17, 0
	s_add_u32 s14, s14, s23
	s_addc_u32 s15, s15, 0
	s_add_u32 s18, s18, s24
	s_addc_u32 s19, s19, 0
	s_add_i32 s22, s22, 1
	s_waitcnt vmcnt(34)
	ds_read_b128 v[216:219], v209 offset:0
	ds_read_b128 v[220:223], v209 offset:64
	ds_read_b128 v[224:227], v209 offset:128
	ds_read_b128 v[228:231], v209 offset:192
	s_waitcnt lgkmcnt(0)
	v_mfma_f32_16x16x32_bf16 v[232:235], v[216:219], v[128:131], 0
	v_mfma_f32_16x16x32_bf16 v[236:239], v[216:219], v[144:147], 0
	v_mfma_f32_16x16x32_bf16 v[232:235], v[220:223], v[132:135], v[232:235]
	v_mfma_f32_16x16x32_bf16 v[236:239], v[220:223], v[148:151], v[236:239]
	v_mfma_f32_16x16x32_bf16 v[232:235], v[224:227], v[136:139], v[232:235]
	v_mfma_f32_16x16x32_bf16 v[236:239], v[224:227], v[152:155], v[236:239]
	v_mfma_f32_16x16x32_bf16 v[232:235], v[228:231], v[140:143], v[232:235]
	v_mfma_f32_16x16x32_bf16 v[236:239], v[228:231], v[156:159], v[236:239]
	s_nop 7
	s_nop 1
	v_lshlrev_b32_e32 v244, 16, v184
	v_and_b32_e32 v245, 0xffff0000, v184
	v_lshlrev_b32_e32 v246, 16, v185
	v_and_b32_e32 v247, 0xffff0000, v185
	v_sub_f32_e32 v244, v244, v232
	v_sub_f32_e32 v245, v245, v233
	v_sub_f32_e32 v246, v246, v234
	v_sub_f32_e32 v247, v247, v235
	v_cvt_pk_bf16_f32 v244, v244, v245
	v_cvt_pk_bf16_f32 v246, v246, v247
	ds_write_b16 v210, v244 offset:0
	ds_write_b16_d16_hi v210, v244 offset:144
	ds_write_b16 v210, v246 offset:288
	ds_write_b16_d16_hi v210, v246 offset:432
	ds_read_b128 v[216:219], v209 offset:6656
	ds_read_b128 v[220:223], v209 offset:6720
	ds_read_b128 v[224:227], v209 offset:6784
	ds_read_b128 v[228:231], v209 offset:6848
	s_waitcnt lgkmcnt(0)
	v_mfma_f32_16x16x32_bf16 v[232:235], v[216:219], v[128:131], 0
	v_mfma_f32_16x16x32_bf16 v[240:243], v[216:219], v[144:147], 0
	v_mfma_f32_16x16x32_bf16 v[232:235], v[220:223], v[132:135], v[232:235]
	v_mfma_f32_16x16x32_bf16 v[240:243], v[220:223], v[148:151], v[240:243]
	v_mfma_f32_16x16x32_bf16 v[232:235], v[224:227], v[136:139], v[232:235]
	v_mfma_f32_16x16x32_bf16 v[240:243], v[224:227], v[152:155], v[240:243]
	v_mfma_f32_16x16x32_bf16 v[232:235], v[228:231], v[140:143], v[232:235]
	v_mfma_f32_16x16x32_bf16 v[240:243], v[228:231], v[156:159], v[240:243]
	s_nop 7
	s_nop 1
	v_lshlrev_b32_e32 v244, 16, v186
	v_and_b32_e32 v245, 0xffff0000, v186
	v_lshlrev_b32_e32 v246, 16, v187
	v_and_b32_e32 v247, 0xffff0000, v187
	v_sub_f32_e32 v244, v244, v232
	v_sub_f32_e32 v245, v245, v233
	v_sub_f32_e32 v246, v246, v234
	v_sub_f32_e32 v247, v247, v235
	v_cvt_pk_bf16_f32 v244, v244, v245
	v_cvt_pk_bf16_f32 v246, v246, v247
	ds_write_b16 v210, v244 offset:6656
	ds_write_b16_d16_hi v210, v244 offset:6800
	ds_write_b16 v210, v246 offset:6944
	ds_write_b16_d16_hi v210, v246 offset:7088
	s_waitcnt lgkmcnt(0)
	s_barrier
	ds_read_b128 v[216:219], v211 offset:0
	ds_read_b128 v[220:223], v211 offset:64
	v_mul_f32_e32 v192, v190, v192
	v_mul_f32_e32 v193, v190, v193
	v_mul_f32_e32 v194, v190, v194
	v_mul_f32_e32 v195, v190, v195
	v_mul_f32_e32 v196, v190, v196
	v_mul_f32_e32 v197, v190, v197
	v_mul_f32_e32 v198, v190, v198
	v_mul_f32_e32 v199, v190, v199
	s_waitcnt lgkmcnt(0)
	v_mfma_f32_16x16x32_bf16 v[236:239], v[216:219], v[160:163], v[236:239]
	v_mfma_f32_16x16x32_bf16 v[192:195], v[216:219], v[168:171], v[192:195]
	v_mfma_f32_16x16x32_bf16 v[196:199], v[216:219], v[176:179], v[196:199]
	v_mfma_f32_16x16x32_bf16 v[236:239], v[220:223], v[164:167], v[236:239]
	v_mfma_f32_16x16x32_bf16 v[192:195], v[220:223], v[172:175], v[192:195]
	v_mfma_f32_16x16x32_bf16 v[196:199], v[220:223], v[180:183], v[196:199]
	s_nop 7
	s_nop 1
	v_cvt_pk_bf16_f32 v244, v236, v237
	v_cvt_pk_bf16_f32 v245, v238, v239
	global_store_dwordx2 v249, v[244:245], s[20:21] offset:0
	v_cvt_pk_bf16_f32 v246, v192, v193
	v_cvt_pk_bf16_f32 v247, v194, v195
	ds_write_b16 v212, v246 offset:0
	ds_write_b16_d16_hi v212, v246 offset:272
	ds_write_b16 v212, v247 offset:544
	ds_write_b16_d16_hi v212, v247 offset:816
	v_cvt_pk_bf16_f32 v246, v196, v197
	v_cvt_pk_bf16_f32 v247, v198, v199
	ds_write_b16 v212, v246 offset:32
	ds_write_b16_d16_hi v212, v246 offset:304
	ds_write_b16 v212, v247 offset:576
	ds_write_b16_d16_hi v212, v247 offset:848
	ds_read_b128 v[216:219], v211 offset:6656
	ds_read_b128 v[220:223], v211 offset:6720
	v_mul_f32_e32 v200, v190, v200
	v_mul_f32_e32 v201, v190, v201
	v_mul_f32_e32 v202, v190, v202
	v_mul_f32_e32 v203, v190, v203
	v_mul_f32_e32 v204, v190, v204
	v_mul_f32_e32 v205, v190, v205
	v_mul_f32_e32 v206, v190, v206
	v_mul_f32_e32 v207, v190, v207
	s_waitcnt lgkmcnt(0)
	v_mfma_f32_16x16x32_bf16 v[240:243], v[216:219], v[160:163], v[240:243]
	v_mfma_f32_16x16x32_bf16 v[200:203], v[216:219], v[168:171], v[200:203]
	v_mfma_f32_16x16x32_bf16 v[204:207], v[216:219], v[176:179], v[204:207]
	v_mfma_f32_16x16x32_bf16 v[240:243], v[220:223], v[164:167], v[240:243]
	v_mfma_f32_16x16x32_bf16 v[200:203], v[220:223], v[172:175], v[200:203]
	v_mfma_f32_16x16x32_bf16 v[204:207], v[220:223], v[180:183], v[204:207]
	s_nop 7
	s_nop 1
	v_cvt_pk_bf16_f32 v244, v240, v241
	v_cvt_pk_bf16_f32 v245, v242, v243
	global_store_dwordx2 v249, v[244:245], s[20:21] offset:32
	v_cvt_pk_bf16_f32 v246, v200, v201
	v_cvt_pk_bf16_f32 v247, v202, v203
	ds_write_b16 v212, v246 offset:6656
	ds_write_b16_d16_hi v212, v246 offset:6928
	ds_write_b16 v212, v247 offset:7200
	ds_write_b16_d16_hi v212, v247 offset:7472
	v_cvt_pk_bf16_f32 v246, v204, v205
	v_cvt_pk_bf16_f32 v247, v206, v207
	ds_write_b16 v212, v246 offset:6688
	ds_write_b16_d16_hi v212, v246 offset:6960
	ds_write_b16 v212, v247 offset:7232
	ds_write_b16_d16_hi v212, v247 offset:7504
	s_add_u32 s20, s20, 0x20000
	s_addc_u32 s21, s21, 0
	s_add_i32 s26, s26, 1
	s_waitcnt lgkmcnt(0)
	s_barrier
	s_cmp_lt_u32 s26, 63
	s_cbranch_scc1 .Lsc_loop
	global_load_dwordx4 v[128:131], v213, s[8:9] offset:0
	global_load_dwordx4 v[132:135], v213, s[8:9] offset:64
	global_load_dwordx4 v[136:139], v213, s[8:9] offset:128
	global_load_dwordx4 v[140:143], v213, s[8:9] offset:192
	global_load_dwordx4 v[144:147], v213, s[10:11] offset:0
	global_load_dwordx4 v[148:151], v213, s[10:11] offset:64
	global_load_dwordx4 v[152:155], v213, s[10:11] offset:128
	global_load_dwordx4 v[156:159], v213, s[10:11] offset:192
	global_load_dwordx4 v[160:163], v214, s[14:15] offset:0
	global_load_dwordx4 v[164:167], v214, s[14:15] offset:64
	global_load_dwordx4 v[168:171], v215, s[12:13] offset:0
	global_load_dwordx4 v[172:175], v215, s[12:13] offset:64
	global_load_dwordx4 v[176:179], v215, s[12:13] offset:2048
	global_load_dwordx4 v[180:183], v215, s[12:13] offset:2112
	global_load_dwordx2 v[184:185], v248, s[16:17] offset:0
	global_load_dwordx2 v[186:187], v248, s[16:17] offset:32
	global_load_dword v190, v250, s[18:19]
	s_cmp_lt_u32 s22, 63
	s_cselect_b32 s0, 0x4000, 0
	s_cselect_b32 s23, 0x2000, 0
	s_cselect_b32 s24, 4, 0
	s_add_u32 s8, s8, s0
	s_addc_u32 s9, s9, 0
	s_add_u32 s10, s10, s0
	s_addc_u32 s11, s11, 0
	s_add_u32 s12, s12, s0
	s_addc_u32 s13, s13, 0
	s_add_u32 s16, s16, s0
	s_addc_u32 s17, s17, 0
	s_add_u32 s14, s14, s23
	s_addc_u32 s15, s15, 0
	s_add_u32 s18, s18, s24
	s_addc_u32 s19, s19, 0
	s_add_i32 s22, s22, 1
	s_waitcnt vmcnt(34)
	ds_read_b128 v[216:219], v209 offset:0
	ds_read_b128 v[220:223], v209 offset:64
	ds_read_b128 v[224:227], v209 offset:128
	ds_read_b128 v[228:231], v209 offset:192
	s_waitcnt lgkmcnt(0)
	v_mfma_f32_16x16x32_bf16 v[232:235], v[216:219], v[0:3], 0
	v_mfma_f32_16x16x32_bf16 v[236:239], v[216:219], v[16:19], 0
	v_mfma_f32_16x16x32_bf16 v[232:235], v[220:223], v[4:7], v[232:235]
	v_mfma_f32_16x16x32_bf16 v[236:239], v[220:223], v[20:23], v[236:239]
	v_mfma_f32_16x16x32_bf16 v[232:235], v[224:227], v[8:11], v[232:235]
	v_mfma_f32_16x16x32_bf16 v[236:239], v[224:227], v[24:27], v[236:239]
	v_mfma_f32_16x16x32_bf16 v[232:235], v[228:231], v[12:15], v[232:235]
	v_mfma_f32_16x16x32_bf16 v[236:239], v[228:231], v[28:31], v[236:239]
	s_nop 7
	s_nop 1
	v_lshlrev_b32_e32 v244, 16, v56
	v_and_b32_e32 v245, 0xffff0000, v56
	v_lshlrev_b32_e32 v246, 16, v57
	v_and_b32_e32 v247, 0xffff0000, v57
	v_sub_f32_e32 v244, v244, v232
	v_sub_f32_e32 v245, v245, v233
	v_sub_f32_e32 v246, v246, v234
	v_sub_f32_e32 v247, v247, v235
	v_cvt_pk_bf16_f32 v244, v244, v245
	v_cvt_pk_bf16_f32 v246, v246, v247
	ds_write_b16 v210, v244 offset:0
	ds_write_b16_d16_hi v210, v244 offset:144
	ds_write_b16 v210, v246 offset:288
	ds_write_b16_d16_hi v210, v246 offset:432
	ds_read_b128 v[216:219], v209 offset:6656
	ds_read_b128 v[220:223], v209 offset:6720
	ds_read_b128 v[224:227], v209 offset:6784
	ds_read_b128 v[228:231], v209 offset:6848
	s_waitcnt lgkmcnt(0)
	v_mfma_f32_16x16x32_bf16 v[232:235], v[216:219], v[0:3], 0
	v_mfma_f32_16x16x32_bf16 v[240:243], v[216:219], v[16:19], 0
	v_mfma_f32_16x16x32_bf16 v[232:235], v[220:223], v[4:7], v[232:235]
	v_mfma_f32_16x16x32_bf16 v[240:243], v[220:223], v[20:23], v[240:243]
	v_mfma_f32_16x16x32_bf16 v[232:235], v[224:227], v[8:11], v[232:235]
	v_mfma_f32_16x16x32_bf16 v[240:243], v[224:227], v[24:27], v[240:243]
	v_mfma_f32_16x16x32_bf16 v[232:235], v[228:231], v[12:15], v[232:235]
	v_mfma_f32_16x16x32_bf16 v[240:243], v[228:231], v[28:31], v[240:243]
	s_nop 7
	s_nop 1
	v_lshlrev_b32_e32 v244, 16, v58
	v_and_b32_e32 v245, 0xffff0000, v58
	v_lshlrev_b32_e32 v246, 16, v59
	v_and_b32_e32 v247, 0xffff0000, v59
	v_sub_f32_e32 v244, v244, v232
	v_sub_f32_e32 v245, v245, v233
	v_sub_f32_e32 v246, v246, v234
	v_sub_f32_e32 v247, v247, v235
	v_cvt_pk_bf16_f32 v244, v244, v245
	v_cvt_pk_bf16_f32 v246, v246, v247
	ds_write_b16 v210, v244 offset:6656
	ds_write_b16_d16_hi v210, v244 offset:6800
	ds_write_b16 v210, v246 offset:6944
	ds_write_b16_d16_hi v210, v246 offset:7088
	s_waitcnt lgkmcnt(0)
	s_barrier
	ds_read_b128 v[216:219], v211 offset:0
	ds_read_b128 v[220:223], v211 offset:64
	v_mul_f32_e32 v192, v62, v192
	v_mul_f32_e32 v193, v62, v193
	v_mul_f32_e32 v194, v62, v194
	v_mul_f32_e32 v195, v62, v195
	v_mul_f32_e32 v196, v62, v196
	v_mul_f32_e32 v197, v62, v197
	v_mul_f32_e32 v198, v62, v198
	v_mul_f32_e32 v199, v62, v199
	s_waitcnt lgkmcnt(0)
	v_mfma_f32_16x16x32_bf16 v[236:239], v[216:219], v[32:35], v[236:239]
	v_mfma_f32_16x16x32_bf16 v[192:195], v[216:219], v[40:43], v[192:195]
	v_mfma_f32_16x16x32_bf16 v[196:199], v[216:219], v[48:51], v[196:199]
	v_mfma_f32_16x16x32_bf16 v[236:239], v[220:223], v[36:39], v[236:239]
	v_mfma_f32_16x16x32_bf16 v[192:195], v[220:223], v[44:47], v[192:195]
	v_mfma_f32_16x16x32_bf16 v[196:199], v[220:223], v[52:55], v[196:199]
	s_nop 7
	s_nop 1
	v_cvt_pk_bf16_f32 v244, v236, v237
	v_cvt_pk_bf16_f32 v245, v238, v239
	global_store_dwordx2 v249, v[244:245], s[20:21] offset:0
	v_cvt_pk_bf16_f32 v246, v192, v193
	v_cvt_pk_bf16_f32 v247, v194, v195
	ds_write_b16 v212, v246 offset:0
	ds_write_b16_d16_hi v212, v246 offset:272
	ds_write_b16 v212, v247 offset:544
	ds_write_b16_d16_hi v212, v247 offset:816
	v_cvt_pk_bf16_f32 v246, v196, v197
	v_cvt_pk_bf16_f32 v247, v198, v199
	ds_write_b16 v212, v246 offset:32
	ds_write_b16_d16_hi v212, v246 offset:304
	ds_write_b16 v212, v247 offset:576
	ds_write_b16_d16_hi v212, v247 offset:848
	ds_read_b128 v[216:219], v211 offset:6656
	ds_read_b128 v[220:223], v211 offset:6720
	v_mul_f32_e32 v200, v62, v200
	v_mul_f32_e32 v201, v62, v201
	v_mul_f32_e32 v202, v62, v202
	v_mul_f32_e32 v203, v62, v203
	v_mul_f32_e32 v204, v62, v204
	v_mul_f32_e32 v205, v62, v205
	v_mul_f32_e32 v206, v62, v206
	v_mul_f32_e32 v207, v62, v207
	s_waitcnt lgkmcnt(0)
	v_mfma_f32_16x16x32_bf16 v[240:243], v[216:219], v[32:35], v[240:243]
	v_mfma_f32_16x16x32_bf16 v[200:203], v[216:219], v[40:43], v[200:203]
	v_mfma_f32_16x16x32_bf16 v[204:207], v[216:219], v[48:51], v[204:207]
	v_mfma_f32_16x16x32_bf16 v[240:243], v[220:223], v[36:39], v[240:243]
	v_mfma_f32_16x16x32_bf16 v[200:203], v[220:223], v[44:47], v[200:203]
	v_mfma_f32_16x16x32_bf16 v[204:207], v[220:223], v[52:55], v[204:207]
	s_nop 7
	s_nop 1
	v_cvt_pk_bf16_f32 v244, v240, v241
	v_cvt_pk_bf16_f32 v245, v242, v243
	global_store_dwordx2 v249, v[244:245], s[20:21] offset:32
	v_cvt_pk_bf16_f32 v246, v200, v201
	v_cvt_pk_bf16_f32 v247, v202, v203
	ds_write_b16 v212, v246 offset:6656
	ds_write_b16_d16_hi v212, v246 offset:6928
	ds_write_b16 v212, v247 offset:7200
	ds_write_b16_d16_hi v212, v247 offset:7472
	v_cvt_pk_bf16_f32 v246, v204, v205
	v_cvt_pk_bf16_f32 v247, v206, v207
	ds_write_b16 v212, v246 offset:6688
	ds_write_b16_d16_hi v212, v246 offset:6960
	ds_write_b16 v212, v247 offset:7232
	ds_write_b16_d16_hi v212, v247 offset:7504
	s_add_u32 s20, s20, 0x20000
	s_addc_u32 s21, s21, 0
	s_add_i32 s26, s26, 1
	s_waitcnt lgkmcnt(0)
	s_barrier
	s_waitcnt vmcnt(0)
	s_add_i32 s27, s27, s95
	s_branch .Lsc_item

